# attention P.V sections (all three loops): per-group lgkmcnt(0) replaced by counted lgkmcnt(6)/(4)/(2)/(0) in front of each MFMA; plus unrolled prologue transposes
# speedup vs baseline: 1.0114x; 1.0114x over previous
; __device__ __forceinline__ void finishSM(f32x16& p0, f32x16& p1, float alpha, float& l_reg, bf16x8& pa0, bf16x8& pa1, bf16x8& pa2, bf16x8& pa3) {
; #pragma unroll
;   for (int r = 0; r < 16; ++r) p1[r] = __builtin_amdgcn_exp2f(p1[r]);
;   float ps = 0;
; #pragma unroll
;   for (int r = 0; r < 16; ++r) ps += p0[r];
; #pragma unroll
;   for (int r = 0; r < 16; ++r) ps += p1[r];
;   { auto rr = __builtin_amdgcn_permlane32_swap(__float_as_uint(ps), __float_as_uint(ps), false, false);
;     ps = __uint_as_float(rr[0]) + __uint_as_float(rr[1]); }
;   l_reg = l_reg * alpha + ps;
;     ...
;   PK4(p0, 0, pa0); PK4(p0, 8, pa1); PK4(p1, 0, pa2); PK4(p1, 8, pa3);
; template <int DQK, int KW, int QSP> __device__ __forceinline__ void qkt(f32x16& p0, f32x16& p1, const char* Ks, const int (&kb)[4], const bf16x8* qr, const char* qsp, const f32x16& cinit) {
;   p0 = cinit; p1 = cinit;
;   constexpr int N = DQK / 16;
;     ...
;   bf16x8 f0[2], f1[2];
;   f0[0] = KRD(0, 1); f1[0] = KRD(0, 0);
; #pragma unroll
;   for (int d0 = 0; d0 < N; ++d0) {
;     if (d0 + 1 < N) { f0[(d0 + 1) & 1] = KRD(d0 + 1, 1); f1[(d0 + 1) & 1] = KRD(d0 + 1, 0); }
;     __builtin_amdgcn_sched_barrier(0x406);
;     bf16x8 qf;
;     if constexpr (QSP > 0) { if (d0 >= N - QSP) qf = *reinterpret_cast<const bf16x8*>(qsp + (d0 - (N - QSP)) * 1024); else qf = qr[d0]; } else qf = qr[d0];
;     p0 = __builtin_amdgcn_mfma_f32_32x32x16_bf16(f0[d0 & 1], qf, p0, 0, 0, 0);
;     p1 = __builtin_amdgcn_mfma_f32_32x32x16_bf16(f1[d0 & 1], qf, p1, 0, 0, 0);
;     __builtin_amdgcn_sched_barrier(0x406); }
.LBB0_51:
	s_mul_i32 s6, s8, 0x6000
	s_add_i32 s6, s6, 0
	v_add_u32_e32 v210, s6, v207
	v_add_u32_e32 v211, s6, v200
	ds_read_b128 v[154:157], v210 offset:49152
	ds_read_b128 v[158:161], v210 offset:61440
	ds_read_b128 v[66:69], v211 offset:61440
	ds_read_b128 v[70:73], v211 offset:49152
	v_add_u32_e32 v223, s6, v205
	v_add_u32_e32 v229, s6, v206
	s_waitcnt lgkmcnt(0)
	v_mfma_f32_32x32x16_bf16 v[82:97], v[70:73], v[130:133], 0
	v_exp_f32_e32 v182, v182
	v_exp_f32_e32 v183, v183
	v_exp_f32_e32 v180, v180
	v_exp_f32_e32 v181, v181
	v_exp_f32_e32 v178, v178
	v_exp_f32_e32 v179, v179
	v_exp_f32_e32 v176, v176
	v_mfma_f32_32x32x16_bf16 v[66:81], v[66:69], v[130:133], 0
	ds_read_b128 v[230:233], v223 offset:49152
	ds_read_b128 v[234:237], v223 offset:61440
	v_exp_f32_e32 v177, v177
	v_exp_f32_e32 v168, v168
	v_exp_f32_e32 v169, v169
	v_exp_f32_e32 v167, v167
	v_mfma_f32_32x32x16_bf16 v[66:81], v[158:161], v[126:129], v[66:81]
	v_mfma_f32_32x32x16_bf16 v[82:97], v[154:157], v[126:129], v[82:97]
	ds_read_b128 v[154:157], v229 offset:49152
	ds_read_b128 v[158:161], v229 offset:61440
	s_waitcnt lgkmcnt(2)
	v_mfma_f32_32x32x16_bf16 v[66:81], v[234:237], v[122:125], v[66:81]
	v_mfma_f32_32x32x16_bf16 v[82:97], v[230:233], v[122:125], v[82:97]
	ds_read_b128 v[230:233], v211 offset:49280
	ds_read_b128 v[234:237], v211 offset:61568
	s_waitcnt lgkmcnt(2)
	v_mfma_f32_32x32x16_bf16 v[66:81], v[158:161], v[118:121], v[66:81]
	v_mfma_f32_32x32x16_bf16 v[82:97], v[154:157], v[118:121], v[82:97]
	ds_read_b128 v[154:157], v210 offset:49280
	ds_read_b128 v[158:161], v210 offset:61568
	s_waitcnt lgkmcnt(2)
	v_mfma_f32_32x32x16_bf16 v[66:81], v[234:237], v[114:117], v[66:81]
	v_mfma_f32_32x32x16_bf16 v[82:97], v[230:233], v[114:117], v[82:97]
	ds_read_b128 v[230:233], v223 offset:49280
	ds_read_b128 v[234:237], v223 offset:61568
	s_waitcnt lgkmcnt(2)
	v_mfma_f32_32x32x16_bf16 v[66:81], v[158:161], v[110:113], v[66:81]
	v_mfma_f32_32x32x16_bf16 v[82:97], v[154:157], v[110:113], v[82:97]
	ds_read_b128 v[154:157], v229 offset:49280
	ds_read_b128 v[158:161], v229 offset:61568
	s_waitcnt lgkmcnt(2)
	v_mfma_f32_32x32x16_bf16 v[66:81], v[234:237], v[106:109], v[66:81]
	v_mfma_f32_32x32x16_bf16 v[82:97], v[230:233], v[106:109], v[82:97]
	ds_read_b128 v[230:233], v211 offset:49408
	ds_read_b128 v[234:237], v211 offset:61696
	s_waitcnt lgkmcnt(2)
	v_mfma_f32_32x32x16_bf16 v[66:81], v[158:161], v[102:105], v[66:81]
	v_mfma_f32_32x32x16_bf16 v[82:97], v[154:157], v[102:105], v[82:97]
	ds_read_b128 v[154:157], v210 offset:49408
	ds_read_b128 v[158:161], v210 offset:61696
	s_waitcnt lgkmcnt(2)
	v_mfma_f32_32x32x16_bf16 v[66:81], v[234:237], v[98:101], v[66:81]
	v_mfma_f32_32x32x16_bf16 v[82:97], v[230:233], v[98:101], v[82:97]
	ds_read_b128 v[230:233], v223 offset:49408
	ds_read_b128 v[234:237], v223 offset:61696
	v_exp_f32_e32 v223, v166
	s_waitcnt lgkmcnt(2)
	v_mfma_f32_32x32x16_bf16 v[66:81], v[158:161], v[248:251], v[66:81]
	v_mfma_f32_32x32x16_bf16 v[82:97], v[154:157], v[248:251], v[82:97]
	ds_read_b128 v[158:161], v229 offset:49408
	ds_read_b128 v[154:157], v229 offset:61696
	ds_read_b128 v[238:241], v197 offset:1024
	v_exp_f32_e32 v229, v164
	s_waitcnt lgkmcnt(0)
	v_mfma_f32_32x32x16_bf16 v[66:81], v[234:237], v[238:241], v[66:81]
	v_mfma_f32_32x32x16_bf16 v[82:97], v[230:233], v[238:241], v[82:97]
	ds_read_b128 v[230:233], v197 offset:2048
	s_waitcnt lgkmcnt(0)
	v_mfma_f32_32x32x16_bf16 v[66:81], v[154:157], v[230:233], v[66:81]
	v_add_f32_e32 v154, 0, v226
	v_add_f32_e32 v154, v228, v154
	v_add_f32_e32 v154, v224, v154
	v_add_f32_e32 v154, v227, v154
	v_add_f32_e32 v154, v221, v154
	v_add_f32_e32 v154, v225, v154
	v_add_f32_e32 v154, v220, v154
	v_add_f32_e32 v154, v222, v154
	v_add_f32_e32 v154, v217, v154
	v_add_f32_e32 v154, v219, v154
	v_add_f32_e32 v154, v215, v154
	v_add_f32_e32 v154, v218, v154
	v_add_f32_e32 v154, v213, v154
	v_add_f32_e32 v154, v216, v154
	v_add_f32_e32 v154, v212, v154
	v_add_f32_e32 v154, v214, v154
	v_add_f32_e32 v154, v182, v154
	v_add_f32_e32 v154, v183, v154
	v_add_f32_e32 v154, v180, v154
	v_add_f32_e32 v154, v181, v154
	v_add_f32_e32 v154, v178, v154
	v_add_f32_e32 v154, v179, v154
	v_add_f32_e32 v154, v176, v154
	v_add_f32_e32 v154, v177, v154
	v_add_f32_e32 v154, v168, v154
	v_mfma_f32_32x32x16_bf16 v[82:97], v[158:161], v[230:233], v[82:97]
	v_exp_f32_e32 v230, v165
	v_add_f32_e32 v154, v169, v154
	v_exp_f32_e32 v231, v162
	v_add_f32_e32 v154, v223, v154
	v_exp_f32_e32 v232, v163
	v_add_f32_e32 v154, v167, v154
	v_add_f32_e32 v154, v229, v154
	v_add_f32_e32 v154, v230, v154
	v_add_f32_e32 v154, v231, v154
	v_add_f32_e32 v210, v232, v154
	v_mov_b32_e32 v211, v210
	v_cvt_pk_bf16_f32 v154, v226, v228
	v_cvt_pk_bf16_f32 v155, v224, v227
	v_cvt_pk_bf16_f32 v156, v221, v225
	s_nop 1
	v_permlane32_swap_b32_e32 v210, v211
	v_cvt_pk_bf16_f32 v157, v220, v222
	v_permlane32_swap_b32_e32 v154, v156
	v_cvt_pk_bf16_f32 v158, v217, v219
	v_cvt_pk_bf16_f32 v159, v215, v218
	v_cvt_pk_bf16_f32 v160, v213, v216
	v_cvt_pk_bf16_f32 v161, v212, v214
	v_cvt_pk_bf16_f32 v162, v182, v183
	v_cvt_pk_bf16_f32 v163, v180, v181
	v_cvt_pk_bf16_f32 v164, v178, v179
	v_cvt_pk_bf16_f32 v165, v176, v177
	v_cvt_pk_bf16_f32 v166, v168, v169
	v_cvt_pk_bf16_f32 v167, v223, v167
	v_cvt_pk_bf16_f32 v168, v229, v230
	v_cvt_pk_bf16_f32 v169, v231, v232
	v_permlane32_swap_b32_e32 v155, v157
	v_permlane32_swap_b32_e32 v158, v160
	v_permlane32_swap_b32_e32 v159, v161
	v_permlane32_swap_b32_e32 v162, v164
	v_permlane32_swap_b32_e32 v163, v165
	v_permlane32_swap_b32_e32 v166, v168
	v_permlane32_swap_b32_e32 v167, v169
	s_lshl_b32 s10, s2, 14
	s_add_i32 s9, s10, 0
	v_add_u32_e32 v176, s9, v201
	s_lshl_b32 s6, s2, 13
	s_waitcnt vmcnt(0)
; #define SBAR() __builtin_amdgcn_sched_barrier(0)
; template <int DQK> __device__ __forceinline__ void partialSM(f32x16& p0, f32x16& p1, float& m_reg, float& mn, float& alpha) {
;   constexpr float SCALE = Sc<DQK>::SCALE; constexpr float C = SCALE * 1.4426950408889634f;
;   float pmax = p0[0];
; #pragma unroll
;   for (int r = 1; r < 16; ++r) pmax = fmaxf(pmax, p0[r]);
; #pragma unroll
;   for (int r = 0; r < 16; ++r) pmax = fmaxf(pmax, p1[r]);
;   { auto rr = __builtin_amdgcn_permlane32_swap(__float_as_uint(pmax), __float_as_uint(pmax), false, false);
;     pmax = fmaxf(__uint_as_float(rr[0]), __uint_as_float(rr[1])); }
;   if (__builtin_expect(__all(pmax - m_reg <= THR / SCALE), 1)) { mn = m_reg; alpha = 1.f; }
;   else { mn = fmaxf(m_reg, pmax); alpha = __builtin_amdgcn_exp2f((m_reg - mn) * C); m_reg = mn; }
; template <int OFF> __device__ __forceinline__ s16x4 tr_read(int vb) {
;   s16x4 r; asm volatile("ds_read_b64_tr_b16 %0, %1 offset:%2" : "=&v"(r) : "v"(vb), "i"(OFF) : "memory"); return r;
; }
; template <int D0> __device__ __forceinline__ void pv_one(f32x16& od, int vb, bf16x8 pa0, bf16x8 pa1, bf16x8 pa2, bf16x8 pa3) {
;   const s16x4 l0 = tr_read<v_rd_off(D0, 0, 0)>(vb), h0 = tr_read<v_rd_off(D0, 0, 1)>(vb), l1 = tr_read<v_rd_off(D0, 1, 0)>(vb), h1 = tr_read<v_rd_off(D0, 1, 1)>(vb);
;   const s16x4 l2 = tr_read<v_rd_off(D0, 2, 0)>(vb), h2 = tr_read<v_rd_off(D0, 2, 1)>(vb), l3 = tr_read<v_rd_off(D0, 3, 0)>(vb), h3 = tr_read<v_rd_off(D0, 3, 1)>(vb);
;   asm volatile("s_waitcnt lgkmcnt(0)" ::: "memory"); SBAR();
;     ...
;   od = __builtin_amdgcn_mfma_f32_32x32x16_bf16(pa0, PK(l0, h0), od, 0, 0, 0);
;   od = __builtin_amdgcn_mfma_f32_32x32x16_bf16(pa1, PK(l1, h1), od, 0, 0, 0);
;   od = __builtin_amdgcn_mfma_f32_32x32x16_bf16(pa2, PK(l2, h2), od, 0, 0, 0);
;   od = __builtin_amdgcn_mfma_f32_32x32x16_bf16(pa3, PK(l3, h3), od, 0, 0, 0);
;     ...
; }
; __device__ __forceinline__ void pv_d0(f32x16* o, int vb, bf16x8 pa0, bf16x8 pa1, bf16x8 pa2, bf16x8 pa3) {
;   pv_one<0>(o[0], vb, pa0, pa1, pa2, pa3); pv_one<1>(o[1], vb, pa0, pa1, pa2, pa3); pv_one<2>(o[2], vb, pa0, pa1, pa2, pa3); pv_one<3>(o[3], vb, pa0, pa1, pa2, pa3);
; }
	s_waitcnt vmcnt(4)
	ds_write_b128 v176, v[134:137]
	v_add_u32_e32 v134, s9, v202
	s_add_i32 s9, s9, s6
	s_waitcnt vmcnt(3)
	ds_write_b128 v134, v[138:141]
	v_add_u32_e32 v134, s9, v203
	s_waitcnt vmcnt(2)
	ds_write_b128 v134, v[142:145] offset:49152
	s_waitcnt vmcnt(1)
	ds_write_b128 v134, v[146:149] offset:61440
	v_add_u32_e32 v134, s9, v204
	v_lshl_add_u64 v[176:177], s[94:95], 0, v[174:175]
	s_mov_b32 s6, 0x198c0000
	s_waitcnt vmcnt(0)
	ds_write_b128 v134, v[150:153] offset:49152
	v_add_co_u32_e32 v134, vcc, s6, v176
	s_mov_b32 s6, 0x198e0000
	s_nop 0
	v_addc_co_u32_e32 v135, vcc, 0, v177, vcc
	v_add_co_u32_e32 v138, vcc, s6, v176
	s_mov_b32 s6, 0x150c0000
	s_nop 0
	v_addc_co_u32_e32 v139, vcc, 0, v177, vcc
	v_add_co_u32_e32 v142, vcc, s6, v176
	s_mov_b32 s6, 0x150e0000
	s_nop 0
	v_addc_co_u32_e32 v143, vcc, 0, v177, vcc
	v_add_co_u32_e32 v146, vcc, s6, v176
	v_lshl_add_u64 v[178:179], s[94:95], 0, v[172:173]
	s_nop 0
	v_addc_co_u32_e32 v147, vcc, 0, v177, vcc
	s_mov_b32 s6, 0x9906000
	v_add_co_u32_e32 v150, vcc, s6, v178
	global_load_dwordx4 v[134:137], v[134:135], off
	s_nop 0
	global_load_dwordx4 v[138:141], v[138:139], off
	v_addc_co_u32_e32 v151, vcc, 0, v179, vcc
	global_load_dwordx4 v[142:145], v[142:143], off
	s_nop 0
	global_load_dwordx4 v[146:149], v[146:147], off
	s_nop 0
	global_load_dwordx4 v[150:153], v[150:151], off
	v_lshl_add_u32 v224, s48, 14, v196
	ds_read_b64_tr_b16 v[180:181], v224 offset:0
	ds_read_b64_tr_b16 v[182:183], v224 offset:0x800
	ds_read_b64_tr_b16 v[212:213], v224 offset:0x1000
	ds_read_b64_tr_b16 v[214:215], v224 offset:0x1800
	ds_read_b64_tr_b16 v[216:217], v224 offset:0x2000
	ds_read_b64_tr_b16 v[218:219], v224 offset:0x2800
	ds_read_b64_tr_b16 v[220:221], v224 offset:0x3000
	ds_read_b64_tr_b16 v[222:223], v224 offset:0x3800
	s_waitcnt lgkmcnt(6)
	s_nop 0
	v_mfma_f32_32x32x16_bf16 v[2:17], v[154:157], v[180:183], v[2:17]
	ds_read_b64_tr_b16 v[180:181], v224 offset:0x200
	ds_read_b64_tr_b16 v[182:183], v224 offset:0xa00
	s_waitcnt lgkmcnt(6)
	v_mfma_f32_32x32x16_bf16 v[2:17], v[158:161], v[212:215], v[2:17]
	ds_read_b64_tr_b16 v[212:213], v224 offset:0x1200
	ds_read_b64_tr_b16 v[214:215], v224 offset:0x1a00
	s_waitcnt lgkmcnt(6)
	v_mfma_f32_32x32x16_bf16 v[2:17], v[162:165], v[216:219], v[2:17]
	ds_read_b64_tr_b16 v[216:217], v224 offset:0x2200
	ds_read_b64_tr_b16 v[218:219], v224 offset:0x2a00
	s_waitcnt lgkmcnt(6)
	v_mfma_f32_32x32x16_bf16 v[2:17], v[166:169], v[220:223], v[2:17]
	ds_read_b64_tr_b16 v[220:221], v224 offset:0x3200
	ds_read_b64_tr_b16 v[222:223], v224 offset:0x3a00
	s_waitcnt lgkmcnt(6)
	v_mfma_f32_32x32x16_bf16 v[50:65], v[154:157], v[180:183], v[50:65]
	ds_read_b64_tr_b16 v[180:181], v224 offset:0x400
	ds_read_b64_tr_b16 v[182:183], v224 offset:0xc00
	s_waitcnt lgkmcnt(6)
	v_mfma_f32_32x32x16_bf16 v[50:65], v[158:161], v[212:215], v[50:65]
	ds_read_b64_tr_b16 v[212:213], v224 offset:0x1400
	ds_read_b64_tr_b16 v[214:215], v224 offset:0x1c00
	s_waitcnt lgkmcnt(6)
	v_mfma_f32_32x32x16_bf16 v[50:65], v[162:165], v[216:219], v[50:65]
	ds_read_b64_tr_b16 v[216:217], v224 offset:0x2400
	ds_read_b64_tr_b16 v[218:219], v224 offset:0x2c00
	s_waitcnt lgkmcnt(6)
	v_mfma_f32_32x32x16_bf16 v[50:65], v[166:169], v[220:223], v[50:65]
	ds_read_b64_tr_b16 v[220:221], v224 offset:0x3400
	ds_read_b64_tr_b16 v[222:223], v224 offset:0x3c00
	s_waitcnt lgkmcnt(6)
	v_mfma_f32_32x32x16_bf16 v[34:49], v[154:157], v[180:183], v[34:49]
	ds_read_b64_tr_b16 v[180:181], v224 offset:0x600
	ds_read_b64_tr_b16 v[182:183], v224 offset:0xe00
	s_waitcnt lgkmcnt(6)
	v_mfma_f32_32x32x16_bf16 v[34:49], v[158:161], v[212:215], v[34:49]
	ds_read_b64_tr_b16 v[212:213], v224 offset:0x1600
	ds_read_b64_tr_b16 v[214:215], v224 offset:0x1e00
	s_waitcnt lgkmcnt(6)
	v_mfma_f32_32x32x16_bf16 v[34:49], v[162:165], v[216:219], v[34:49]
	ds_read_b64_tr_b16 v[216:217], v224 offset:0x2600
	ds_read_b64_tr_b16 v[218:219], v224 offset:0x2e00
	s_waitcnt lgkmcnt(6)
	v_mfma_f32_32x32x16_bf16 v[34:49], v[166:169], v[220:223], v[34:49]
	ds_read_b64_tr_b16 v[220:221], v224 offset:0x3600
	ds_read_b64_tr_b16 v[222:223], v224 offset:0x3e00
	s_waitcnt lgkmcnt(6)
	v_mfma_f32_32x32x16_bf16 v[18:33], v[154:157], v[180:183], v[18:33]
	v_max_f32_e32 v154, v83, v83
	v_max_f32_e32 v155, v82, v82
	v_max_f32_e32 v154, v155, v154
	v_max3_f32 v154, v154, v84, v85
	v_max3_f32 v154, v154, v86, v87
	v_max3_f32 v154, v154, v88, v89
	v_max3_f32 v154, v154, v90, v91
	v_max3_f32 v154, v154, v92, v93
	v_max3_f32 v154, v154, v94, v95
	s_waitcnt lgkmcnt(4)
	v_mfma_f32_32x32x16_bf16 v[18:33], v[158:161], v[212:215], v[18:33]
	v_max3_f32 v154, v154, v96, v97
	v_max3_f32 v154, v154, v66, v67
	v_max3_f32 v154, v154, v68, v69
	v_max3_f32 v154, v154, v70, v71
	v_max3_f32 v154, v154, v72, v73
	v_max3_f32 v154, v154, v74, v75
	v_max3_f32 v154, v154, v76, v77
	v_max3_f32 v154, v154, v78, v79
	s_waitcnt lgkmcnt(2)
	v_mfma_f32_32x32x16_bf16 v[18:33], v[162:165], v[216:219], v[18:33]
	v_max3_f32 v154, v154, v80, v81
	v_mov_b32_e32 v155, v154
	s_nop 1
	v_permlane32_swap_b32_e32 v154, v155
	v_max_f32_e32 v155, v155, v155
	v_max_f32_e32 v154, v154, v154
	v_max_f32_e32 v154, v154, v155
	v_sub_f32_e32 v155, v154, v209
	v_cmp_ge_f32_e32 vcc, s49, v155
	v_max_f32_e32 v155, v209, v209
	v_max_f32_e32 v154, v155, v154
	s_waitcnt lgkmcnt(0)
	v_mfma_f32_32x32x16_bf16 v[18:33], v[166:169], v[220:223], v[18:33]
	v_sub_f32_e32 v155, v209, v154
	v_mul_f32_e32 v155, 0x3dd53b94, v155
	v_exp_f32_e32 v155, v155
	s_cmp_eq_u64 vcc, exec
	s_cselect_b64 s[40:41], -1, 0
	s_waitcnt lgkmcnt(0)
	s_barrier
	v_cndmask_b32_e64 v223, v155, 1.0, s[40:41]
	v_cmp_gt_f32_e32 vcc, 1.0, v223
	s_cbranch_vccz .LBB0_55
	s_and_saveexec_b64 s[6:7], s[38:39]
	ds_write_b32 v198, v223 offset:128
	s_or_b64 exec, exec, s[6:7]
	s_waitcnt lgkmcnt(0)
	v_add_u32_e32 v155, v195, v170
	ds_read_b128 v[156:159], v155 offset:224
	ds_read_b128 v[160:163], v155 offset:192
	ds_read_b128 v[164:167], v155 offset:160
	ds_read_b128 v[180:183], v155 offset:128
	s_waitcnt lgkmcnt(3)
	v_pk_mul_f32 v[14:15], v[14:15], v[156:157]
	s_waitcnt lgkmcnt(2)
	v_pk_mul_f32 v[10:11], v[10:11], v[160:161]
	s_waitcnt lgkmcnt(1)
	v_pk_mul_f32 v[6:7], v[6:7], v[164:165]
	v_pk_mul_f32 v[16:17], v[16:17], v[158:159]
	v_pk_mul_f32 v[12:13], v[12:13], v[162:163]
	v_pk_mul_f32 v[8:9], v[8:9], v[166:167]
	s_waitcnt lgkmcnt(0)
	v_pk_mul_f32 v[4:5], v[4:5], v[182:183]
	v_pk_mul_f32 v[2:3], v[2:3], v[180:181]
	v_pk_mul_f32 v[62:63], v[62:63], v[156:157]
	v_pk_mul_f32 v[58:59], v[58:59], v[160:161]
	v_pk_mul_f32 v[54:55], v[54:55], v[164:165]
	v_pk_mul_f32 v[64:65], v[64:65], v[158:159]
	v_pk_mul_f32 v[60:61], v[60:61], v[162:163]
	v_pk_mul_f32 v[56:57], v[56:57], v[166:167]
	v_pk_mul_f32 v[52:53], v[52:53], v[182:183]
	v_pk_mul_f32 v[50:51], v[50:51], v[180:181]
	v_pk_mul_f32 v[46:47], v[46:47], v[156:157]
	v_pk_mul_f32 v[42:43], v[42:43], v[160:161]
	v_pk_mul_f32 v[38:39], v[38:39], v[164:165]
	v_pk_mul_f32 v[48:49], v[48:49], v[158:159]
	v_pk_mul_f32 v[44:45], v[44:45], v[162:163]
	v_pk_mul_f32 v[40:41], v[40:41], v[166:167]
	v_pk_mul_f32 v[36:37], v[36:37], v[182:183]
	v_pk_mul_f32 v[34:35], v[34:35], v[180:181]
	v_pk_mul_f32 v[30:31], v[30:31], v[156:157]
	v_pk_mul_f32 v[26:27], v[26:27], v[160:161]
	v_pk_mul_f32 v[22:23], v[22:23], v[164:165]
	v_pk_mul_f32 v[32:33], v[32:33], v[158:159]
	v_pk_mul_f32 v[28:29], v[28:29], v[162:163]
	v_pk_mul_f32 v[24:25], v[24:25], v[166:167]
	v_pk_mul_f32 v[20:21], v[20:21], v[182:183]
	v_pk_mul_f32 v[18:19], v[18:19], v[180:181]

; #define SBAR() __builtin_amdgcn_sched_barrier(0)
; template <int DQK> __device__ __forceinline__ void partialSM(f32x16& p0, f32x16& p1, float& m_reg, float& mn, float& alpha) {
;   constexpr float SCALE = Sc<DQK>::SCALE; constexpr float C = SCALE * 1.4426950408889634f;
;   float pmax = p0[0];
; #pragma unroll
;   for (int r = 1; r < 16; ++r) pmax = fmaxf(pmax, p0[r]);
; #pragma unroll
;   for (int r = 0; r < 16; ++r) pmax = fmaxf(pmax, p1[r]);
;   { auto rr = __builtin_amdgcn_permlane32_swap(__float_as_uint(pmax), __float_as_uint(pmax), false, false);
;     pmax = fmaxf(__uint_as_float(rr[0]), __uint_as_float(rr[1])); }
;   if (__builtin_expect(__all(pmax - m_reg <= THR / SCALE), 1)) { mn = m_reg; alpha = 1.f; }
;   else { mn = fmaxf(m_reg, pmax); alpha = __builtin_amdgcn_exp2f((m_reg - mn) * C); m_reg = mn; }
; template <int OFF> __device__ __forceinline__ s16x4 tr_read(int vb) {
;   s16x4 r; asm volatile("ds_read_b64_tr_b16 %0, %1 offset:%2" : "=&v"(r) : "v"(vb), "i"(OFF) : "memory"); return r;
; }
; template <int D0> __device__ __forceinline__ void pv_one(f32x16& od, int vb, bf16x8 pa0, bf16x8 pa1, bf16x8 pa2, bf16x8 pa3) {
;   const s16x4 l0 = tr_read<v_rd_off(D0, 0, 0)>(vb), h0 = tr_read<v_rd_off(D0, 0, 1)>(vb), l1 = tr_read<v_rd_off(D0, 1, 0)>(vb), h1 = tr_read<v_rd_off(D0, 1, 1)>(vb);
;   const s16x4 l2 = tr_read<v_rd_off(D0, 2, 0)>(vb), h2 = tr_read<v_rd_off(D0, 2, 1)>(vb), l3 = tr_read<v_rd_off(D0, 3, 0)>(vb), h3 = tr_read<v_rd_off(D0, 3, 1)>(vb);
;   asm volatile("s_waitcnt lgkmcnt(0)" ::: "memory"); SBAR();
;     ...
;   od = __builtin_amdgcn_mfma_f32_32x32x16_bf16(pa0, PK(l0, h0), od, 0, 0, 0);
;   od = __builtin_amdgcn_mfma_f32_32x32x16_bf16(pa1, PK(l1, h1), od, 0, 0, 0);
;   od = __builtin_amdgcn_mfma_f32_32x32x16_bf16(pa2, PK(l2, h2), od, 0, 0, 0);
;   od = __builtin_amdgcn_mfma_f32_32x32x16_bf16(pa3, PK(l3, h3), od, 0, 0, 0);
;     ...
; }
; __device__ __forceinline__ void pv_d0(f32x16* o, int vb, bf16x8 pa0, bf16x8 pa1, bf16x8 pa2, bf16x8 pa3) {
;   pv_one<0>(o[0], vb, pa0, pa1, pa2, pa3); pv_one<1>(o[1], vb, pa0, pa1, pa2, pa3); pv_one<2>(o[2], vb, pa0, pa1, pa2, pa3); pv_one<3>(o[3], vb, pa0, pa1, pa2, pa3);
; }
.LBB0_57:
	v_lshl_add_u32 v181, s8, 14, v196
	ds_read_b64_tr_b16 v[176:177], v181 offset:0
	ds_read_b64_tr_b16 v[178:179], v181 offset:0x800
	ds_read_b64_tr_b16 v[212:213], v181 offset:0x1000
	ds_read_b64_tr_b16 v[214:215], v181 offset:0x1800
	ds_read_b64_tr_b16 v[216:217], v181 offset:0x2000
	ds_read_b64_tr_b16 v[218:219], v181 offset:0x2800
	ds_read_b64_tr_b16 v[224:225], v181 offset:0x3000
	ds_read_b64_tr_b16 v[226:227], v181 offset:0x3800
	s_waitcnt lgkmcnt(6)
	s_nop 0
	v_mfma_f32_32x32x16_bf16 v[2:17], v[154:157], v[176:179], v[2:17]
	ds_read_b64_tr_b16 v[176:177], v181 offset:0x200
	ds_read_b64_tr_b16 v[178:179], v181 offset:0xa00
	s_waitcnt lgkmcnt(6)
	v_mfma_f32_32x32x16_bf16 v[2:17], v[158:161], v[212:215], v[2:17]
	ds_read_b64_tr_b16 v[212:213], v181 offset:0x1200
	ds_read_b64_tr_b16 v[214:215], v181 offset:0x1a00
	s_waitcnt lgkmcnt(6)
	v_mfma_f32_32x32x16_bf16 v[2:17], v[162:165], v[216:219], v[2:17]
	ds_read_b64_tr_b16 v[216:217], v181 offset:0x2200
	ds_read_b64_tr_b16 v[218:219], v181 offset:0x2a00
	s_waitcnt lgkmcnt(6)
	v_mfma_f32_32x32x16_bf16 v[2:17], v[166:169], v[224:227], v[2:17]
	ds_read_b64_tr_b16 v[224:225], v181 offset:0x3200
	ds_read_b64_tr_b16 v[226:227], v181 offset:0x3a00
	s_waitcnt lgkmcnt(6)
	v_mfma_f32_32x32x16_bf16 v[50:65], v[154:157], v[176:179], v[50:65]
	ds_read_b64_tr_b16 v[176:177], v181 offset:0x400
	ds_read_b64_tr_b16 v[178:179], v181 offset:0xc00
	s_waitcnt lgkmcnt(6)
	v_mfma_f32_32x32x16_bf16 v[50:65], v[158:161], v[212:215], v[50:65]
	ds_read_b64_tr_b16 v[212:213], v181 offset:0x1400
	ds_read_b64_tr_b16 v[214:215], v181 offset:0x1c00
	s_waitcnt lgkmcnt(6)
	v_mfma_f32_32x32x16_bf16 v[50:65], v[162:165], v[216:219], v[50:65]
	ds_read_b64_tr_b16 v[216:217], v181 offset:0x2400
	ds_read_b64_tr_b16 v[218:219], v181 offset:0x2c00
	s_waitcnt lgkmcnt(6)
	v_mfma_f32_32x32x16_bf16 v[50:65], v[166:169], v[224:227], v[50:65]
	ds_read_b64_tr_b16 v[224:225], v181 offset:0x3400
	ds_read_b64_tr_b16 v[226:227], v181 offset:0x3c00
	s_waitcnt lgkmcnt(6)
	v_mfma_f32_32x32x16_bf16 v[34:49], v[154:157], v[176:179], v[34:49]
	ds_read_b64_tr_b16 v[176:177], v181 offset:0x600
	ds_read_b64_tr_b16 v[178:179], v181 offset:0xe00
	s_waitcnt lgkmcnt(6)
	v_mfma_f32_32x32x16_bf16 v[34:49], v[158:161], v[212:215], v[34:49]
	ds_read_b64_tr_b16 v[212:213], v181 offset:0x1600
	ds_read_b64_tr_b16 v[214:215], v181 offset:0x1e00
	s_waitcnt lgkmcnt(6)
	v_mfma_f32_32x32x16_bf16 v[34:49], v[162:165], v[216:219], v[34:49]
	ds_read_b64_tr_b16 v[216:217], v181 offset:0x2600
	ds_read_b64_tr_b16 v[218:219], v181 offset:0x2e00
	s_waitcnt lgkmcnt(6)
	v_mfma_f32_32x32x16_bf16 v[34:49], v[166:169], v[224:227], v[34:49]
	ds_read_b64_tr_b16 v[224:225], v181 offset:0x3600
	ds_read_b64_tr_b16 v[226:227], v181 offset:0x3e00
	s_waitcnt lgkmcnt(6)
	v_mfma_f32_32x32x16_bf16 v[18:33], v[154:157], v[176:179], v[18:33]
	v_max_f32_e32 v154, v83, v83
	v_max_f32_e32 v155, v82, v82
	v_max_f32_e32 v154, v155, v154
	v_max3_f32 v154, v154, v84, v85
	v_max3_f32 v154, v154, v86, v87
	v_max3_f32 v154, v154, v88, v89
	v_max3_f32 v154, v154, v90, v91
	v_max3_f32 v154, v154, v92, v93
	v_max3_f32 v154, v154, v94, v95
	s_waitcnt lgkmcnt(4)
	v_mfma_f32_32x32x16_bf16 v[18:33], v[158:161], v[212:215], v[18:33]
	v_max3_f32 v154, v154, v96, v97
	v_max3_f32 v154, v154, v66, v67
	v_max3_f32 v154, v154, v68, v69
	v_max3_f32 v154, v154, v70, v71
	v_max3_f32 v154, v154, v72, v73
	v_max3_f32 v154, v154, v74, v75
	v_max3_f32 v154, v154, v76, v77
	v_max3_f32 v154, v154, v78, v79
	s_waitcnt lgkmcnt(2)
	v_mfma_f32_32x32x16_bf16 v[18:33], v[162:165], v[216:219], v[18:33]
	v_max3_f32 v154, v154, v80, v81
	v_mov_b32_e32 v155, v154
	s_nop 1
	v_permlane32_swap_b32_e32 v154, v155
	v_max_f32_e32 v155, v155, v155
	v_max_f32_e32 v154, v154, v154
	v_max_f32_e32 v154, v154, v155
	v_sub_f32_e32 v155, v154, v180
	v_cmp_ge_f32_e32 vcc, s49, v155
	v_max_f32_e32 v155, v180, v180
	v_max_f32_e32 v154, v155, v154
	s_waitcnt lgkmcnt(0)
	v_mfma_f32_32x32x16_bf16 v[18:33], v[166:169], v[224:227], v[18:33]
	v_sub_f32_e32 v155, v180, v154
	v_mul_f32_e32 v155, 0x3dd53b94, v155
	v_exp_f32_e32 v155, v155
	s_cmp_eq_u64 vcc, exec
	s_cselect_b64 s[40:41], -1, 0
	s_waitcnt lgkmcnt(0)
	s_barrier
	v_cndmask_b32_e64 v155, v155, 1.0, s[40:41]
	v_cmp_gt_f32_e32 vcc, 1.0, v155
	s_cbranch_vccz .LBB0_61
	s_and_saveexec_b64 s[8:9], s[38:39]
	ds_write_b32 v198, v155 offset:128
	s_or_b64 exec, exec, s[8:9]
	s_waitcnt lgkmcnt(0)
	v_add_u32_e32 v168, v195, v170
	ds_read_b128 v[156:159], v168 offset:224
	ds_read_b128 v[160:163], v168 offset:192
	ds_read_b128 v[164:167], v168 offset:160
	ds_read_b128 v[176:179], v168 offset:128
	s_waitcnt lgkmcnt(3)
	v_pk_mul_f32 v[14:15], v[14:15], v[156:157]
	s_waitcnt lgkmcnt(2)
	v_pk_mul_f32 v[10:11], v[10:11], v[160:161]
	s_waitcnt lgkmcnt(1)
	v_pk_mul_f32 v[6:7], v[6:7], v[164:165]
	v_pk_mul_f32 v[16:17], v[16:17], v[158:159]
	v_pk_mul_f32 v[12:13], v[12:13], v[162:163]
	v_pk_mul_f32 v[8:9], v[8:9], v[166:167]
	s_waitcnt lgkmcnt(0)
	v_pk_mul_f32 v[4:5], v[4:5], v[178:179]
	v_pk_mul_f32 v[2:3], v[2:3], v[176:177]
	v_pk_mul_f32 v[62:63], v[62:63], v[156:157]
	v_pk_mul_f32 v[58:59], v[58:59], v[160:161]
	v_pk_mul_f32 v[54:55], v[54:55], v[164:165]
	v_pk_mul_f32 v[64:65], v[64:65], v[158:159]
	v_pk_mul_f32 v[60:61], v[60:61], v[162:163]
	v_pk_mul_f32 v[56:57], v[56:57], v[166:167]
	v_pk_mul_f32 v[52:53], v[52:53], v[178:179]
	v_pk_mul_f32 v[50:51], v[50:51], v[176:177]
	v_pk_mul_f32 v[46:47], v[46:47], v[156:157]
	v_pk_mul_f32 v[42:43], v[42:43], v[160:161]
	v_pk_mul_f32 v[38:39], v[38:39], v[164:165]
	v_pk_mul_f32 v[48:49], v[48:49], v[158:159]
	v_pk_mul_f32 v[44:45], v[44:45], v[162:163]
	v_pk_mul_f32 v[40:41], v[40:41], v[166:167]
	v_pk_mul_f32 v[36:37], v[36:37], v[178:179]
	v_pk_mul_f32 v[34:35], v[34:35], v[176:177]
	v_pk_mul_f32 v[30:31], v[30:31], v[156:157]
	v_pk_mul_f32 v[26:27], v[26:27], v[160:161]
	v_pk_mul_f32 v[22:23], v[22:23], v[164:165]
	v_pk_mul_f32 v[32:33], v[32:33], v[158:159]
	v_pk_mul_f32 v[28:29], v[28:29], v[162:163]
	v_pk_mul_f32 v[24:25], v[24:25], v[166:167]
	v_pk_mul_f32 v[20:21], v[20:21], v[178:179]
	v_pk_mul_f32 v[18:19], v[18:19], v[176:177]

; __device__ __forceinline__ void finishSM(f32x16& p0, f32x16& p1, float alpha, float& l_reg, bf16x8& pa0, bf16x8& pa1, bf16x8& pa2, bf16x8& pa3) {
; #pragma unroll
;   for (int r = 0; r < 16; ++r) p1[r] = __builtin_amdgcn_exp2f(p1[r]);
;   float ps = 0;
; #pragma unroll
;   for (int r = 0; r < 16; ++r) ps += p0[r];
; #pragma unroll
;   for (int r = 0; r < 16; ++r) ps += p1[r];
;   { auto rr = __builtin_amdgcn_permlane32_swap(__float_as_uint(ps), __float_as_uint(ps), false, false);
;     ps = __uint_as_float(rr[0]) + __uint_as_float(rr[1]); }
;   l_reg = l_reg * alpha + ps;
;     ...
;   PK4(p0, 0, pa0); PK4(p0, 8, pa1); PK4(p1, 0, pa2); PK4(p1, 8, pa3);
; template <int DQK, int KW, int QSP> __device__ __forceinline__ void qkt(f32x16& p0, f32x16& p1, const char* Ks, const int (&kb)[4], const bf16x8* qr, const char* qsp, const f32x16& cinit) {
;   p0 = cinit; p1 = cinit;
;   constexpr int N = DQK / 16;
;     ...
;   bf16x8 f0[2], f1[2];
;   f0[0] = KRD(0, 1); f1[0] = KRD(0, 0);
; #pragma unroll
;   for (int d0 = 0; d0 < N; ++d0) {
;     if (d0 + 1 < N) { f0[(d0 + 1) & 1] = KRD(d0 + 1, 1); f1[(d0 + 1) & 1] = KRD(d0 + 1, 0); }
;     __builtin_amdgcn_sched_barrier(0x406);
;     bf16x8 qf;
;     if constexpr (QSP > 0) { if (d0 >= N - QSP) qf = *reinterpret_cast<const bf16x8*>(qsp + (d0 - (N - QSP)) * 1024); else qf = qr[d0]; } else qf = qr[d0];
;     p0 = __builtin_amdgcn_mfma_f32_32x32x16_bf16(f0[d0 & 1], qf, p0, 0, 0, 0);
;     p1 = __builtin_amdgcn_mfma_f32_32x32x16_bf16(f1[d0 & 1], qf, p1, 0, 0, 0);
;     __builtin_amdgcn_sched_barrier(0x406); }
.LBB0_286:
	s_lshl_b32 s8, s30, 14
	s_add_i32 s6, s8, 0
	v_add_u32_e32 v208, s6, v163
	v_add_u32_e32 v209, s6, v158
	ds_read_b128 v[168:171], v208 offset:49152
	ds_read_b128 v[196:199], v208 offset:57344
	ds_read_b128 v[66:69], v209 offset:57344
	ds_read_b128 v[70:73], v209 offset:49152
	v_add_u32_e32 v212, s6, v164
	v_add_u32_e32 v213, s6, v165
	s_waitcnt lgkmcnt(0)
	v_mfma_f32_32x32x16_bf16 v[82:97], v[70:73], v[102:105], 0
	v_exp_f32_e32 v144, v144
	v_exp_f32_e32 v145, v145
	v_exp_f32_e32 v142, v142
	v_exp_f32_e32 v143, v143
	v_exp_f32_e32 v140, v140
	v_exp_f32_e32 v141, v141
	v_mfma_f32_32x32x16_bf16 v[66:81], v[66:69], v[102:105], 0
	ds_read_b128 v[200:203], v212 offset:49152
	ds_read_b128 v[204:207], v212 offset:57344
	v_mfma_f32_32x32x16_bf16 v[82:97], v[168:171], v[110:113], v[82:97]
	v_mfma_f32_32x32x16_bf16 v[66:81], v[196:199], v[110:113], v[66:81]
	ds_read_b128 v[168:171], v213 offset:49152
	ds_read_b128 v[196:199], v213 offset:57344
	s_waitcnt lgkmcnt(3)
	v_mfma_f32_32x32x16_bf16 v[82:97], v[200:203], v[106:109], v[82:97]
	s_waitcnt lgkmcnt(2)
	v_mfma_f32_32x32x16_bf16 v[66:81], v[204:207], v[106:109], v[66:81]
	ds_read_b128 v[200:203], v209 offset:49280
	ds_read_b128 v[204:207], v209 offset:57472
	s_waitcnt lgkmcnt(3)
	v_mfma_f32_32x32x16_bf16 v[82:97], v[168:171], v[98:101], v[82:97]
	s_waitcnt lgkmcnt(2)
	v_mfma_f32_32x32x16_bf16 v[66:81], v[196:199], v[98:101], v[66:81]
	ds_read_b128 v[168:171], v208 offset:49280
	ds_read_b128 v[196:199], v208 offset:57472
	s_waitcnt lgkmcnt(3)
	v_mfma_f32_32x32x16_bf16 v[82:97], v[200:203], v[220:223], v[82:97]
	s_waitcnt lgkmcnt(2)
	v_mfma_f32_32x32x16_bf16 v[66:81], v[204:207], v[220:223], v[66:81]
	ds_read_b128 v[200:203], v212 offset:49280
	ds_read_b128 v[204:207], v212 offset:57472
	s_waitcnt lgkmcnt(3)
	v_mfma_f32_32x32x16_bf16 v[82:97], v[168:171], v[224:227], v[82:97]
	s_waitcnt lgkmcnt(2)
	v_mfma_f32_32x32x16_bf16 v[66:81], v[196:199], v[224:227], v[66:81]
	ds_read_b128 v[168:171], v213 offset:49280
	ds_read_b128 v[196:199], v213 offset:57472
	s_waitcnt lgkmcnt(3)
	v_mfma_f32_32x32x16_bf16 v[82:97], v[200:203], v[228:231], v[82:97]
	s_waitcnt lgkmcnt(2)
	v_mfma_f32_32x32x16_bf16 v[66:81], v[204:207], v[228:231], v[66:81]
	s_waitcnt lgkmcnt(0)
	v_mfma_f32_32x32x16_bf16 v[82:97], v[168:171], v[232:235], v[82:97]
	v_exp_f32_e32 v170, v138
	v_exp_f32_e32 v171, v139
	v_mfma_f32_32x32x16_bf16 v[66:81], v[196:199], v[232:235], v[66:81]
	v_exp_f32_e32 v202, v130
	v_add_f32_e32 v130, 0, v193
	v_add_f32_e32 v130, v195, v130
	v_add_f32_e32 v130, v183, v130
	v_add_f32_e32 v130, v194, v130
	v_add_f32_e32 v130, v181, v130
	v_add_f32_e32 v130, v192, v130
	v_add_f32_e32 v130, v180, v130
	v_add_f32_e32 v130, v182, v130
	v_add_f32_e32 v130, v177, v130
	v_add_f32_e32 v130, v179, v130
	v_add_f32_e32 v130, v175, v130
	v_add_f32_e32 v130, v178, v130
	v_add_f32_e32 v130, v173, v130
	v_add_f32_e32 v130, v176, v130
	v_add_f32_e32 v130, v172, v130
	v_add_f32_e32 v130, v174, v130
	v_add_f32_e32 v130, v144, v130
	v_add_f32_e32 v130, v145, v130
	v_add_f32_e32 v130, v142, v130
	v_add_f32_e32 v130, v143, v130
	v_exp_f32_e32 v196, v136
	v_add_f32_e32 v130, v140, v130
	v_exp_f32_e32 v197, v137
	v_add_f32_e32 v130, v141, v130
	v_exp_f32_e32 v198, v134
	v_add_f32_e32 v130, v170, v130
	v_exp_f32_e32 v199, v135
	v_add_f32_e32 v130, v171, v130
	v_exp_f32_e32 v200, v132
	v_add_f32_e32 v130, v196, v130
	v_exp_f32_e32 v201, v133
	v_add_f32_e32 v130, v197, v130
	v_add_f32_e32 v130, v198, v130
	v_exp_f32_e32 v203, v131
	v_add_f32_e32 v130, v199, v130
	v_add_f32_e32 v130, v200, v130
	v_add_f32_e32 v130, v201, v130
	v_add_f32_e32 v130, v202, v130
	v_add_f32_e32 v168, v203, v130
	v_mov_b32_e32 v169, v168
	v_cvt_pk_bf16_f32 v130, v193, v195
	v_cvt_pk_bf16_f32 v131, v183, v194
	v_cvt_pk_bf16_f32 v132, v181, v192
	s_nop 1
	v_permlane32_swap_b32_e32 v168, v169
	v_cvt_pk_bf16_f32 v133, v180, v182
	v_permlane32_swap_b32_e32 v130, v132
	v_cvt_pk_bf16_f32 v134, v177, v179
	v_cvt_pk_bf16_f32 v135, v175, v178
	v_cvt_pk_bf16_f32 v136, v173, v176
	v_cvt_pk_bf16_f32 v137, v172, v174
	v_cvt_pk_bf16_f32 v138, v144, v145
	v_cvt_pk_bf16_f32 v139, v142, v143
	v_cvt_pk_bf16_f32 v140, v140, v141
	v_cvt_pk_bf16_f32 v141, v170, v171
	v_cvt_pk_bf16_f32 v142, v196, v197
	v_cvt_pk_bf16_f32 v143, v198, v199
	v_cvt_pk_bf16_f32 v144, v200, v201
	v_cvt_pk_bf16_f32 v145, v202, v203
	v_permlane32_swap_b32_e32 v131, v133
	v_permlane32_swap_b32_e32 v134, v136
	v_permlane32_swap_b32_e32 v135, v137
	v_permlane32_swap_b32_e32 v138, v140
	v_permlane32_swap_b32_e32 v139, v141
	v_permlane32_swap_b32_e32 v142, v144
	v_permlane32_swap_b32_e32 v143, v145
	s_lshl_b32 s28, s27, 14
	s_add_i32 s9, s28, 0
	v_add_u32_e32 v170, s9, v159
	s_waitcnt vmcnt(0)
	s_waitcnt vmcnt(3)
	ds_write_b128 v170, v[114:117]
	v_add_u32_e32 v114, s9, v160
	s_waitcnt vmcnt(1)
	ds_write_b128 v114, v[118:121]
	v_add_u32_e32 v114, s9, v161
	s_mov_b32 s6, 0xfffe8000
	s_waitcnt vmcnt(1)
	ds_write_b128 v114, v[122:125] offset:49152
	s_waitcnt vmcnt(0)
	ds_write_b128 v114, v[126:129] offset:57344
	v_add_co_u32_e32 v114, vcc, s6, v148
	s_mov_b32 s6, 0xfb7e8000
	s_nop 0
	v_addc_co_u32_e32 v115, vcc, -1, v149, vcc
	v_add_co_u32_e32 v118, vcc, s3, v148
	s_nop 1
	v_addc_co_u32_e32 v119, vcc, -1, v149, vcc
	v_add_co_u32_e32 v122, vcc, s6, v148
	s_mov_b32 s6, 0xfb7f0000
	s_nop 0
	v_addc_co_u32_e32 v123, vcc, -1, v149, vcc
	v_add_co_u32_e32 v126, vcc, s6, v148
	global_load_dwordx4 v[114:117], v[114:115], off
	s_nop 0
	global_load_dwordx4 v[118:121], v[118:119], off
	v_addc_co_u32_e32 v127, vcc, -1, v149, vcc
	global_load_dwordx4 v[122:125], v[122:123], off
	s_nop 0
	global_load_dwordx4 v[126:129], v[126:127], off
	v_lshl_add_u32 v182, s48, 14, v154
	ds_read_b64_tr_b16 v[170:171], v182 offset:0
	ds_read_b64_tr_b16 v[172:173], v182 offset:0x800
	ds_read_b64_tr_b16 v[174:175], v182 offset:0x1000
	ds_read_b64_tr_b16 v[176:177], v182 offset:0x1800
	ds_read_b64_tr_b16 v[178:179], v182 offset:0x2000
	ds_read_b64_tr_b16 v[180:181], v182 offset:0x2800
	ds_read_b64_tr_b16 v[192:193], v182 offset:0x3000
	ds_read_b64_tr_b16 v[194:195], v182 offset:0x3800
	s_waitcnt lgkmcnt(6)
; #define SBAR() __builtin_amdgcn_sched_barrier(0)
; template <int DQK> __device__ __forceinline__ void partialSM(f32x16& p0, f32x16& p1, float& m_reg, float& mn, float& alpha) {
;   constexpr float SCALE = Sc<DQK>::SCALE; constexpr float C = SCALE * 1.4426950408889634f;
;   float pmax = p0[0];
; #pragma unroll
;   for (int r = 1; r < 16; ++r) pmax = fmaxf(pmax, p0[r]);
; #pragma unroll
;   for (int r = 0; r < 16; ++r) pmax = fmaxf(pmax, p1[r]);
;   { auto rr = __builtin_amdgcn_permlane32_swap(__float_as_uint(pmax), __float_as_uint(pmax), false, false);
;     pmax = fmaxf(__uint_as_float(rr[0]), __uint_as_float(rr[1])); }
;   if (__builtin_expect(__all(pmax - m_reg <= THR / SCALE), 1)) { mn = m_reg; alpha = 1.f; }
;   else { mn = fmaxf(m_reg, pmax); alpha = __builtin_amdgcn_exp2f((m_reg - mn) * C); m_reg = mn; }
; template <int D0> __device__ __forceinline__ void pv_one(f32x16& od, int vb, bf16x8 pa0, bf16x8 pa1, bf16x8 pa2, bf16x8 pa3) {
;   const s16x4 l0 = tr_read<v_rd_off(D0, 0, 0)>(vb), h0 = tr_read<v_rd_off(D0, 0, 1)>(vb), l1 = tr_read<v_rd_off(D0, 1, 0)>(vb), h1 = tr_read<v_rd_off(D0, 1, 1)>(vb);
;   const s16x4 l2 = tr_read<v_rd_off(D0, 2, 0)>(vb), h2 = tr_read<v_rd_off(D0, 2, 1)>(vb), l3 = tr_read<v_rd_off(D0, 3, 0)>(vb), h3 = tr_read<v_rd_off(D0, 3, 1)>(vb);
;   asm volatile("s_waitcnt lgkmcnt(0)" ::: "memory"); SBAR();
;     ...
;   od = __builtin_amdgcn_mfma_f32_32x32x16_bf16(pa0, PK(l0, h0), od, 0, 0, 0);
;   od = __builtin_amdgcn_mfma_f32_32x32x16_bf16(pa1, PK(l1, h1), od, 0, 0, 0);
;   od = __builtin_amdgcn_mfma_f32_32x32x16_bf16(pa2, PK(l2, h2), od, 0, 0, 0);
;   od = __builtin_amdgcn_mfma_f32_32x32x16_bf16(pa3, PK(l3, h3), od, 0, 0, 0);
;     ...
; }
	s_nop 0
	v_mfma_f32_32x32x16_bf16 v[2:17], v[130:133], v[170:173], v[2:17]
	ds_read_b64_tr_b16 v[170:171], v182 offset:0x200
	ds_read_b64_tr_b16 v[172:173], v182 offset:0xa00
	s_waitcnt lgkmcnt(6)
	v_mfma_f32_32x32x16_bf16 v[2:17], v[134:137], v[174:177], v[2:17]
	ds_read_b64_tr_b16 v[174:175], v182 offset:0x1200
	ds_read_b64_tr_b16 v[176:177], v182 offset:0x1a00
	s_waitcnt lgkmcnt(6)
	v_mfma_f32_32x32x16_bf16 v[2:17], v[138:141], v[178:181], v[2:17]
	ds_read_b64_tr_b16 v[178:179], v182 offset:0x2200
	ds_read_b64_tr_b16 v[180:181], v182 offset:0x2a00
	s_waitcnt lgkmcnt(6)
	v_mfma_f32_32x32x16_bf16 v[2:17], v[142:145], v[192:195], v[2:17]
	ds_read_b64_tr_b16 v[192:193], v182 offset:0x3200
	ds_read_b64_tr_b16 v[194:195], v182 offset:0x3a00
	s_waitcnt lgkmcnt(6)
	v_mfma_f32_32x32x16_bf16 v[50:65], v[130:133], v[170:173], v[50:65]
	ds_read_b64_tr_b16 v[170:171], v182 offset:0x400
	ds_read_b64_tr_b16 v[172:173], v182 offset:0xc00
	s_waitcnt lgkmcnt(6)
	v_mfma_f32_32x32x16_bf16 v[50:65], v[134:137], v[174:177], v[50:65]
	ds_read_b64_tr_b16 v[174:175], v182 offset:0x1400
	ds_read_b64_tr_b16 v[176:177], v182 offset:0x1c00
	s_waitcnt lgkmcnt(6)
	v_mfma_f32_32x32x16_bf16 v[50:65], v[138:141], v[178:181], v[50:65]
	ds_read_b64_tr_b16 v[178:179], v182 offset:0x2400
	ds_read_b64_tr_b16 v[180:181], v182 offset:0x2c00
	s_waitcnt lgkmcnt(6)
	v_mfma_f32_32x32x16_bf16 v[50:65], v[142:145], v[192:195], v[50:65]
	ds_read_b64_tr_b16 v[192:193], v182 offset:0x3400
	ds_read_b64_tr_b16 v[194:195], v182 offset:0x3c00
	s_waitcnt lgkmcnt(6)
	v_mfma_f32_32x32x16_bf16 v[34:49], v[130:133], v[170:173], v[34:49]
	ds_read_b64_tr_b16 v[170:171], v182 offset:0x600
	ds_read_b64_tr_b16 v[172:173], v182 offset:0xe00
	s_waitcnt lgkmcnt(6)
	v_mfma_f32_32x32x16_bf16 v[34:49], v[134:137], v[174:177], v[34:49]
	ds_read_b64_tr_b16 v[174:175], v182 offset:0x1600
	ds_read_b64_tr_b16 v[176:177], v182 offset:0x1e00
	s_waitcnt lgkmcnt(6)
	v_mfma_f32_32x32x16_bf16 v[34:49], v[138:141], v[178:181], v[34:49]
	ds_read_b64_tr_b16 v[178:179], v182 offset:0x2600
	ds_read_b64_tr_b16 v[180:181], v182 offset:0x2e00
	s_waitcnt lgkmcnt(6)
	v_mfma_f32_32x32x16_bf16 v[34:49], v[142:145], v[192:195], v[34:49]
	ds_read_b64_tr_b16 v[192:193], v182 offset:0x3600
	ds_read_b64_tr_b16 v[194:195], v182 offset:0x3e00
	s_waitcnt lgkmcnt(6)
	v_mfma_f32_32x32x16_bf16 v[18:33], v[130:133], v[170:173], v[18:33]
	v_max_f32_e32 v130, v83, v83
	v_max_f32_e32 v131, v82, v82
	v_max_f32_e32 v130, v131, v130
	v_max3_f32 v130, v130, v84, v85
	v_max3_f32 v130, v130, v86, v87
	v_max3_f32 v130, v130, v88, v89
	v_max3_f32 v130, v130, v90, v91
	v_max3_f32 v130, v130, v92, v93
	v_max3_f32 v130, v130, v94, v95
	s_waitcnt lgkmcnt(4)
	v_mfma_f32_32x32x16_bf16 v[18:33], v[134:137], v[174:177], v[18:33]
	v_max3_f32 v130, v130, v96, v97
	v_max3_f32 v130, v130, v66, v67
	v_max3_f32 v130, v130, v68, v69
	v_max3_f32 v130, v130, v70, v71
	v_max3_f32 v130, v130, v72, v73
	v_max3_f32 v130, v130, v74, v75
	v_max3_f32 v130, v130, v76, v77
	v_max3_f32 v130, v130, v78, v79
	s_waitcnt lgkmcnt(2)
	v_mfma_f32_32x32x16_bf16 v[18:33], v[138:141], v[178:181], v[18:33]
	v_max3_f32 v130, v130, v80, v81
	v_mov_b32_e32 v131, v130
	s_nop 1
	v_permlane32_swap_b32_e32 v130, v131
	v_max_f32_e32 v131, v131, v131
	v_max_f32_e32 v130, v130, v130
	v_max_f32_e32 v130, v130, v131
	v_sub_f32_e32 v131, v130, v167
	v_cmp_ge_f32_e32 vcc, s33, v131
	v_max_f32_e32 v131, v167, v167
	v_max_f32_e32 v130, v131, v130
	s_waitcnt lgkmcnt(0)
	v_mfma_f32_32x32x16_bf16 v[18:33], v[142:145], v[192:195], v[18:33]
	v_sub_f32_e32 v131, v167, v130
	v_mul_f32_e32 v131, 0x3e0293ee, v131
	v_exp_f32_e32 v131, v131
	s_cmp_eq_u64 vcc, exec
	s_cselect_b64 s[40:41], -1, 0
	s_waitcnt lgkmcnt(0)
	s_barrier
	v_cndmask_b32_e64 v171, v131, 1.0, s[40:41]
	v_cmp_gt_f32_e32 vcc, 1.0, v171
	s_cbranch_vccz .LBB0_290
	s_and_saveexec_b64 s[6:7], s[38:39]
	ds_write_b32 v155, v171 offset:128
	s_or_b64 exec, exec, s[6:7]
	s_waitcnt lgkmcnt(0)
	v_add_u32_e32 v131, v153, v146
	ds_read_b128 v[132:135], v131 offset:224
	ds_read_b128 v[136:139], v131 offset:192
	ds_read_b128 v[140:143], v131 offset:160
	ds_read_b128 v[172:175], v131 offset:128
	s_waitcnt lgkmcnt(3)
	v_pk_mul_f32 v[14:15], v[14:15], v[132:133]
	s_waitcnt lgkmcnt(2)
	v_pk_mul_f32 v[10:11], v[10:11], v[136:137]
	s_waitcnt lgkmcnt(1)
	v_pk_mul_f32 v[6:7], v[6:7], v[140:141]
	v_pk_mul_f32 v[16:17], v[16:17], v[134:135]
	v_pk_mul_f32 v[12:13], v[12:13], v[138:139]
	v_pk_mul_f32 v[8:9], v[8:9], v[142:143]
	s_waitcnt lgkmcnt(0)
	v_pk_mul_f32 v[4:5], v[4:5], v[174:175]
	v_pk_mul_f32 v[2:3], v[2:3], v[172:173]
	v_pk_mul_f32 v[62:63], v[62:63], v[132:133]
	v_pk_mul_f32 v[58:59], v[58:59], v[136:137]
	v_pk_mul_f32 v[54:55], v[54:55], v[140:141]
	v_pk_mul_f32 v[64:65], v[64:65], v[134:135]
	v_pk_mul_f32 v[60:61], v[60:61], v[138:139]
	v_pk_mul_f32 v[56:57], v[56:57], v[142:143]
	v_pk_mul_f32 v[52:53], v[52:53], v[174:175]
	v_pk_mul_f32 v[50:51], v[50:51], v[172:173]
	v_pk_mul_f32 v[46:47], v[46:47], v[132:133]
	v_pk_mul_f32 v[42:43], v[42:43], v[136:137]
	v_pk_mul_f32 v[38:39], v[38:39], v[140:141]
	v_pk_mul_f32 v[48:49], v[48:49], v[134:135]
	v_pk_mul_f32 v[44:45], v[44:45], v[138:139]
	v_pk_mul_f32 v[40:41], v[40:41], v[142:143]
	v_pk_mul_f32 v[36:37], v[36:37], v[174:175]
	v_pk_mul_f32 v[34:35], v[34:35], v[172:173]
	v_pk_mul_f32 v[30:31], v[30:31], v[132:133]
	v_pk_mul_f32 v[26:27], v[26:27], v[136:137]
	v_pk_mul_f32 v[22:23], v[22:23], v[140:141]
	v_pk_mul_f32 v[32:33], v[32:33], v[134:135]
	v_pk_mul_f32 v[28:29], v[28:29], v[138:139]
	v_pk_mul_f32 v[24:25], v[24:25], v[142:143]
	v_pk_mul_f32 v[20:21], v[20:21], v[174:175]
	v_pk_mul_f32 v[18:19], v[18:19], v[172:173]

; #define SBAR() __builtin_amdgcn_sched_barrier(0)
; template <int DQK> __device__ __forceinline__ void partialSM(f32x16& p0, f32x16& p1, float& m_reg, float& mn, float& alpha) {
;   constexpr float SCALE = Sc<DQK>::SCALE; constexpr float C = SCALE * 1.4426950408889634f;
;   float pmax = p0[0];
; #pragma unroll
;   for (int r = 1; r < 16; ++r) pmax = fmaxf(pmax, p0[r]);
; #pragma unroll
;   for (int r = 0; r < 16; ++r) pmax = fmaxf(pmax, p1[r]);
;   { auto rr = __builtin_amdgcn_permlane32_swap(__float_as_uint(pmax), __float_as_uint(pmax), false, false);
;     pmax = fmaxf(__uint_as_float(rr[0]), __uint_as_float(rr[1])); }
;   if (__builtin_expect(__all(pmax - m_reg <= THR / SCALE), 1)) { mn = m_reg; alpha = 1.f; }
;   else { mn = fmaxf(m_reg, pmax); alpha = __builtin_amdgcn_exp2f((m_reg - mn) * C); m_reg = mn; }
; template <int D0> __device__ __forceinline__ void pv_one(f32x16& od, int vb, bf16x8 pa0, bf16x8 pa1, bf16x8 pa2, bf16x8 pa3) {
;   const s16x4 l0 = tr_read<v_rd_off(D0, 0, 0)>(vb), h0 = tr_read<v_rd_off(D0, 0, 1)>(vb), l1 = tr_read<v_rd_off(D0, 1, 0)>(vb), h1 = tr_read<v_rd_off(D0, 1, 1)>(vb);
;   const s16x4 l2 = tr_read<v_rd_off(D0, 2, 0)>(vb), h2 = tr_read<v_rd_off(D0, 2, 1)>(vb), l3 = tr_read<v_rd_off(D0, 3, 0)>(vb), h3 = tr_read<v_rd_off(D0, 3, 1)>(vb);
;   asm volatile("s_waitcnt lgkmcnt(0)" ::: "memory"); SBAR();
;     ...
;   od = __builtin_amdgcn_mfma_f32_32x32x16_bf16(pa0, PK(l0, h0), od, 0, 0, 0);
;   od = __builtin_amdgcn_mfma_f32_32x32x16_bf16(pa1, PK(l1, h1), od, 0, 0, 0);
;   od = __builtin_amdgcn_mfma_f32_32x32x16_bf16(pa2, PK(l2, h2), od, 0, 0, 0);
;   od = __builtin_amdgcn_mfma_f32_32x32x16_bf16(pa3, PK(l3, h3), od, 0, 0, 0);
;     ...
; }
.LBB0_292:
	v_add_u32_e32 v170, s8, v154
	ds_read_b64_tr_b16 v[172:173], v170 offset:0
	ds_read_b64_tr_b16 v[174:175], v170 offset:0x800
	ds_read_b64_tr_b16 v[176:177], v170 offset:0x1000
	ds_read_b64_tr_b16 v[178:179], v170 offset:0x1800
	ds_read_b64_tr_b16 v[180:181], v170 offset:0x2000
	ds_read_b64_tr_b16 v[182:183], v170 offset:0x2800
	ds_read_b64_tr_b16 v[192:193], v170 offset:0x3000
	ds_read_b64_tr_b16 v[194:195], v170 offset:0x3800
	s_waitcnt lgkmcnt(6)
	s_nop 0
	v_mfma_f32_32x32x16_bf16 v[2:17], v[130:133], v[172:175], v[2:17]
	ds_read_b64_tr_b16 v[172:173], v170 offset:0x200
	ds_read_b64_tr_b16 v[174:175], v170 offset:0xa00
	s_waitcnt lgkmcnt(6)
	v_mfma_f32_32x32x16_bf16 v[2:17], v[134:137], v[176:179], v[2:17]
	ds_read_b64_tr_b16 v[176:177], v170 offset:0x1200
	ds_read_b64_tr_b16 v[178:179], v170 offset:0x1a00
	s_waitcnt lgkmcnt(6)
	v_mfma_f32_32x32x16_bf16 v[2:17], v[138:141], v[180:183], v[2:17]
	ds_read_b64_tr_b16 v[180:181], v170 offset:0x2200
	ds_read_b64_tr_b16 v[182:183], v170 offset:0x2a00
	s_waitcnt lgkmcnt(6)
	v_mfma_f32_32x32x16_bf16 v[2:17], v[142:145], v[192:195], v[2:17]
	ds_read_b64_tr_b16 v[192:193], v170 offset:0x3200
	ds_read_b64_tr_b16 v[194:195], v170 offset:0x3a00
	s_waitcnt lgkmcnt(6)
	v_mfma_f32_32x32x16_bf16 v[50:65], v[130:133], v[172:175], v[50:65]
	ds_read_b64_tr_b16 v[172:173], v170 offset:0x400
	ds_read_b64_tr_b16 v[174:175], v170 offset:0xc00
	s_waitcnt lgkmcnt(6)
	v_mfma_f32_32x32x16_bf16 v[50:65], v[134:137], v[176:179], v[50:65]
	ds_read_b64_tr_b16 v[176:177], v170 offset:0x1400
	ds_read_b64_tr_b16 v[178:179], v170 offset:0x1c00
	s_waitcnt lgkmcnt(6)
	v_mfma_f32_32x32x16_bf16 v[50:65], v[138:141], v[180:183], v[50:65]
	ds_read_b64_tr_b16 v[180:181], v170 offset:0x2400
	ds_read_b64_tr_b16 v[182:183], v170 offset:0x2c00
	s_waitcnt lgkmcnt(6)
	v_mfma_f32_32x32x16_bf16 v[50:65], v[142:145], v[192:195], v[50:65]
	ds_read_b64_tr_b16 v[192:193], v170 offset:0x3400
	ds_read_b64_tr_b16 v[194:195], v170 offset:0x3c00
	s_waitcnt lgkmcnt(6)
	v_mfma_f32_32x32x16_bf16 v[34:49], v[130:133], v[172:175], v[34:49]
	ds_read_b64_tr_b16 v[172:173], v170 offset:0x600
	ds_read_b64_tr_b16 v[174:175], v170 offset:0xe00
	s_waitcnt lgkmcnt(6)
	v_mfma_f32_32x32x16_bf16 v[34:49], v[134:137], v[176:179], v[34:49]
	ds_read_b64_tr_b16 v[176:177], v170 offset:0x1600
	ds_read_b64_tr_b16 v[178:179], v170 offset:0x1e00
	s_waitcnt lgkmcnt(6)
	v_mfma_f32_32x32x16_bf16 v[34:49], v[138:141], v[180:183], v[34:49]
	ds_read_b64_tr_b16 v[180:181], v170 offset:0x2600
	ds_read_b64_tr_b16 v[182:183], v170 offset:0x2e00
	s_waitcnt lgkmcnt(6)
	v_mfma_f32_32x32x16_bf16 v[34:49], v[142:145], v[192:195], v[34:49]
	ds_read_b64_tr_b16 v[192:193], v170 offset:0x3600
	ds_read_b64_tr_b16 v[194:195], v170 offset:0x3e00
	s_waitcnt lgkmcnt(6)
	v_mfma_f32_32x32x16_bf16 v[18:33], v[130:133], v[172:175], v[18:33]
	v_max_f32_e32 v130, v83, v83
	v_max_f32_e32 v131, v82, v82
	v_max_f32_e32 v130, v131, v130
	v_max3_f32 v130, v130, v84, v85
	v_max3_f32 v130, v130, v86, v87
	v_max3_f32 v130, v130, v88, v89
	v_max3_f32 v130, v130, v90, v91
	v_max3_f32 v130, v130, v92, v93
	v_max3_f32 v130, v130, v94, v95
	s_waitcnt lgkmcnt(4)
	v_mfma_f32_32x32x16_bf16 v[18:33], v[134:137], v[176:179], v[18:33]
	v_max3_f32 v130, v130, v96, v97
	v_max3_f32 v130, v130, v66, v67
	v_max3_f32 v130, v130, v68, v69
	v_max3_f32 v130, v130, v70, v71
	v_max3_f32 v130, v130, v72, v73
	v_max3_f32 v130, v130, v74, v75
	v_max3_f32 v130, v130, v76, v77
	v_max3_f32 v130, v130, v78, v79
	s_waitcnt lgkmcnt(2)
	v_mfma_f32_32x32x16_bf16 v[18:33], v[138:141], v[180:183], v[18:33]
	v_max3_f32 v130, v130, v80, v81
	v_mov_b32_e32 v131, v130
	s_nop 1
	v_permlane32_swap_b32_e32 v130, v131
	v_max_f32_e32 v131, v131, v131
	v_max_f32_e32 v130, v130, v130
	v_max_f32_e32 v130, v130, v131
	v_sub_f32_e32 v131, v130, v167
	v_cmp_ge_f32_e32 vcc, s33, v131
	v_max_f32_e32 v131, v167, v167
	v_max_f32_e32 v130, v131, v130
	s_waitcnt lgkmcnt(0)
	v_mfma_f32_32x32x16_bf16 v[18:33], v[142:145], v[192:195], v[18:33]
	v_sub_f32_e32 v131, v167, v130
	v_mul_f32_e32 v131, 0x3e0293ee, v131
	v_exp_f32_e32 v131, v131
	s_cmp_eq_u64 vcc, exec
	s_cselect_b64 s[40:41], -1, 0
	s_waitcnt lgkmcnt(0)
	s_barrier
	v_cndmask_b32_e64 v170, v131, 1.0, s[40:41]
	v_cmp_gt_f32_e32 vcc, 1.0, v170
	s_cbranch_vccz .LBB0_296
	s_and_saveexec_b64 s[8:9], s[38:39]
	ds_write_b32 v155, v170 offset:128
	s_or_b64 exec, exec, s[8:9]
	s_waitcnt lgkmcnt(0)
	v_add_u32_e32 v131, v153, v146
	ds_read_b128 v[132:135], v131 offset:224
	ds_read_b128 v[136:139], v131 offset:192
	ds_read_b128 v[140:143], v131 offset:160
	ds_read_b128 v[172:175], v131 offset:128
	s_waitcnt lgkmcnt(3)
	v_pk_mul_f32 v[14:15], v[14:15], v[132:133]
	s_waitcnt lgkmcnt(2)
	v_pk_mul_f32 v[10:11], v[10:11], v[136:137]
	s_waitcnt lgkmcnt(1)
	v_pk_mul_f32 v[6:7], v[6:7], v[140:141]
	v_pk_mul_f32 v[16:17], v[16:17], v[134:135]
	v_pk_mul_f32 v[12:13], v[12:13], v[138:139]
	v_pk_mul_f32 v[8:9], v[8:9], v[142:143]
	s_waitcnt lgkmcnt(0)
	v_pk_mul_f32 v[4:5], v[4:5], v[174:175]
	v_pk_mul_f32 v[2:3], v[2:3], v[172:173]
	v_pk_mul_f32 v[62:63], v[62:63], v[132:133]
	v_pk_mul_f32 v[58:59], v[58:59], v[136:137]
	v_pk_mul_f32 v[54:55], v[54:55], v[140:141]
	v_pk_mul_f32 v[64:65], v[64:65], v[134:135]
	v_pk_mul_f32 v[60:61], v[60:61], v[138:139]
	v_pk_mul_f32 v[56:57], v[56:57], v[142:143]
	v_pk_mul_f32 v[52:53], v[52:53], v[174:175]
	v_pk_mul_f32 v[50:51], v[50:51], v[172:173]
	v_pk_mul_f32 v[46:47], v[46:47], v[132:133]
	v_pk_mul_f32 v[42:43], v[42:43], v[136:137]
	v_pk_mul_f32 v[38:39], v[38:39], v[140:141]
	v_pk_mul_f32 v[48:49], v[48:49], v[134:135]
	v_pk_mul_f32 v[44:45], v[44:45], v[138:139]
	v_pk_mul_f32 v[40:41], v[40:41], v[142:143]
	v_pk_mul_f32 v[36:37], v[36:37], v[174:175]
	v_pk_mul_f32 v[34:35], v[34:35], v[172:173]
	v_pk_mul_f32 v[30:31], v[30:31], v[132:133]
	v_pk_mul_f32 v[26:27], v[26:27], v[136:137]
	v_pk_mul_f32 v[22:23], v[22:23], v[140:141]
	v_pk_mul_f32 v[32:33], v[32:33], v[134:135]
	v_pk_mul_f32 v[28:29], v[28:29], v[138:139]
	v_pk_mul_f32 v[24:25], v[24:25], v[142:143]
	v_pk_mul_f32 v[20:21], v[20:21], v[174:175]
	v_pk_mul_f32 v[18:19], v[18:19], v[172:173]

; __device__ __forceinline__ void finishSM(f32x16& p0, f32x16& p1, float alpha, float& l_reg, bf16x8& pa0, bf16x8& pa1, bf16x8& pa2, bf16x8& pa3) {
; #pragma unroll
;   for (int r = 0; r < 16; ++r) p1[r] = __builtin_amdgcn_exp2f(p1[r]);
;   float ps = 0;
; #pragma unroll
;   for (int r = 0; r < 16; ++r) ps += p0[r];
; #pragma unroll
;   for (int r = 0; r < 16; ++r) ps += p1[r];
;   { auto rr = __builtin_amdgcn_permlane32_swap(__float_as_uint(ps), __float_as_uint(ps), false, false);
;     ps = __uint_as_float(rr[0]) + __uint_as_float(rr[1]); }
;   l_reg = l_reg * alpha + ps;
;     ...
;   PK4(p0, 0, pa0); PK4(p0, 8, pa1); PK4(p1, 0, pa2); PK4(p1, 8, pa3);
;     ...
; }
; template <int DQK, int KW, int QSP> __device__ __forceinline__ void qkt(f32x16& p0, f32x16& p1, const char* Ks, const int (&kb)[4], const bf16x8* qr, const char* qsp, const f32x16& cinit) {
;   p0 = cinit; p1 = cinit;
;   constexpr int N = DQK / 16;
;     ...
;   bf16x8 f0[2], f1[2];
;   f0[0] = KRD(0, 1); f1[0] = KRD(0, 0);
; #pragma unroll
;   for (int d0 = 0; d0 < N; ++d0) {
;     if (d0 + 1 < N) { f0[(d0 + 1) & 1] = KRD(d0 + 1, 1); f1[(d0 + 1) & 1] = KRD(d0 + 1, 0); }
;     __builtin_amdgcn_sched_barrier(0x406);
;     bf16x8 qf;
;     if constexpr (QSP > 0) { if (d0 >= N - QSP) qf = *reinterpret_cast<const bf16x8*>(qsp + (d0 - (N - QSP)) * 1024); else qf = qr[d0]; } else qf = qr[d0];
;     p0 = __builtin_amdgcn_mfma_f32_32x32x16_bf16(f0[d0 & 1], qf, p0, 0, 0, 0);
;     p1 = __builtin_amdgcn_mfma_f32_32x32x16_bf16(f1[d0 & 1], qf, p1, 0, 0, 0);
;     __builtin_amdgcn_sched_barrier(0x406); }
;     ...
; }
.LBB0_316:
	s_lshl_b32 s10, s35, 14
	s_add_i32 s8, s10, 0
	v_add_u32_e32 v102, s8, v183
	ds_read_b128 v[98:101], v102 offset:49152
	v_add_u32_e32 v103, s8, v197
	ds_read_b128 v[200:203], v102 offset:57344
	ds_read_b128 v[222:225], v103 offset:49152
	ds_read_b128 v[226:229], v103 offset:57344
	v_add_u32_e32 v204, s8, v196
	v_exp_f32_e32 v205, v85
	v_exp_f32_e32 v97, v97
	s_waitcnt lgkmcnt(3)
	v_mfma_f32_32x32x16_bf16 v[114:129], v[98:101], v[142:145], v[66:81]
	s_waitcnt lgkmcnt(2)
	v_mfma_f32_32x32x16_bf16 v[98:113], v[200:203], v[142:145], v[66:81]
	ds_read_b128 v[200:203], v204 offset:49152
	ds_read_b128 v[230:233], v204 offset:57344
	v_add_u32_e32 v204, s8, v198
	s_waitcnt lgkmcnt(3)
	v_mfma_f32_32x32x16_bf16 v[114:129], v[222:225], v[138:141], v[114:129]
	s_waitcnt lgkmcnt(2)
	v_mfma_f32_32x32x16_bf16 v[98:113], v[226:229], v[138:141], v[98:113]
	ds_read_b128 v[222:225], v204 offset:49152
	ds_read_b128 v[226:229], v204 offset:57344
	v_exp_f32_e32 v204, v84
	s_waitcnt lgkmcnt(3)
	v_mfma_f32_32x32x16_bf16 v[114:129], v[200:203], v[134:137], v[114:129]
	v_exp_f32_e32 v202, v82
	v_add_f32_e32 v82, 0, v219
	v_add_f32_e32 v82, v221, v82
	v_add_f32_e32 v82, v217, v82
	v_add_f32_e32 v82, v220, v82
	v_add_f32_e32 v82, v215, v82
	v_add_f32_e32 v82, v218, v82
	v_add_f32_e32 v82, v214, v82
	v_add_f32_e32 v82, v216, v82
	v_add_f32_e32 v82, v211, v82
	v_add_f32_e32 v82, v213, v82
	v_add_f32_e32 v82, v209, v82
	v_add_f32_e32 v82, v212, v82
	s_waitcnt lgkmcnt(2)
	v_mfma_f32_32x32x16_bf16 v[98:113], v[230:233], v[134:137], v[98:113]
	v_add_f32_e32 v82, v207, v82
	v_exp_f32_e32 v203, v83
	v_add_f32_e32 v82, v210, v82
	v_add_f32_e32 v82, v206, v82
	v_add_f32_e32 v82, v208, v82
	v_add_f32_e32 v82, v202, v82
	v_add_f32_e32 v82, v203, v82
	s_waitcnt lgkmcnt(1)
	v_mfma_f32_32x32x16_bf16 v[114:129], v[222:225], v[130:133], v[114:129]
	v_exp_f32_e32 v222, v86
	v_exp_f32_e32 v223, v87
	v_exp_f32_e32 v224, v88
	v_add_f32_e32 v82, v204, v82
	v_exp_f32_e32 v225, v89
	v_add_f32_e32 v82, v205, v82
	v_add_f32_e32 v82, v222, v82
	s_waitcnt lgkmcnt(0)
	v_mfma_f32_32x32x16_bf16 v[98:113], v[226:229], v[130:133], v[98:113]
	v_exp_f32_e32 v226, v90
	v_exp_f32_e32 v227, v91
	v_add_f32_e32 v82, v223, v82
	v_exp_f32_e32 v228, v92
	v_add_f32_e32 v82, v224, v82
	v_exp_f32_e32 v229, v93
	v_add_f32_e32 v82, v225, v82
	v_exp_f32_e32 v230, v94
	v_add_f32_e32 v82, v226, v82
	v_exp_f32_e32 v231, v95
	v_add_f32_e32 v82, v227, v82
	v_exp_f32_e32 v232, v96
	v_add_f32_e32 v82, v228, v82
	v_add_f32_e32 v82, v229, v82
	v_add_f32_e32 v82, v230, v82
	v_add_f32_e32 v82, v231, v82
	v_add_f32_e32 v82, v232, v82
	v_add_f32_e32 v200, v97, v82
	v_mov_b32_e32 v201, v200
	v_cvt_pk_bf16_f32 v82, v219, v221
	v_cvt_pk_bf16_f32 v83, v217, v220
	v_cvt_pk_bf16_f32 v84, v215, v218
	s_nop 1
	v_permlane32_swap_b32_e32 v200, v201
	v_cvt_pk_bf16_f32 v85, v214, v216
	v_permlane32_swap_b32_e32 v82, v84
	v_cvt_pk_bf16_f32 v86, v211, v213
	v_cvt_pk_bf16_f32 v87, v209, v212
	v_cvt_pk_bf16_f32 v88, v207, v210
	v_cvt_pk_bf16_f32 v89, v206, v208
	v_cvt_pk_bf16_f32 v90, v202, v203
	v_cvt_pk_bf16_f32 v91, v204, v205
	v_cvt_pk_bf16_f32 v92, v222, v223
	v_cvt_pk_bf16_f32 v93, v224, v225
	v_cvt_pk_bf16_f32 v94, v226, v227
	v_cvt_pk_bf16_f32 v95, v228, v229
	v_cvt_pk_bf16_f32 v96, v230, v231
	v_cvt_pk_bf16_f32 v97, v232, v97
	v_permlane32_swap_b32_e32 v83, v85
	v_permlane32_swap_b32_e32 v86, v88
	v_permlane32_swap_b32_e32 v87, v89
	v_permlane32_swap_b32_e32 v90, v92
	v_permlane32_swap_b32_e32 v91, v93
	v_permlane32_swap_b32_e32 v94, v96
	v_permlane32_swap_b32_e32 v95, v97
	s_lshl_b32 s13, s12, 14
	s_add_i32 s11, s13, 0
	v_add_u32_e32 v202, s11, v192
	s_waitcnt vmcnt(0)
	s_waitcnt vmcnt(3)
	ds_write_b128 v202, v[146:149]
	v_add_u32_e32 v146, s11, v193
	s_waitcnt vmcnt(1)
	ds_write_b128 v146, v[150:153]
	v_add_u32_e32 v146, s11, v194
	s_mov_b32 s8, 0xfffa0000
	s_waitcnt vmcnt(1)
	ds_write_b128 v146, v[154:157] offset:49152
	s_waitcnt vmcnt(0)
; #define SBAR() __builtin_amdgcn_sched_barrier(0)
; template <int D0> __device__ __forceinline__ void pv_one(f32x16& od, int vb, bf16x8 pa0, bf16x8 pa1, bf16x8 pa2, bf16x8 pa3) {
;   const s16x4 l0 = tr_read<v_rd_off(D0, 0, 0)>(vb), h0 = tr_read<v_rd_off(D0, 0, 1)>(vb), l1 = tr_read<v_rd_off(D0, 1, 0)>(vb), h1 = tr_read<v_rd_off(D0, 1, 1)>(vb);
;   const s16x4 l2 = tr_read<v_rd_off(D0, 2, 0)>(vb), h2 = tr_read<v_rd_off(D0, 2, 1)>(vb), l3 = tr_read<v_rd_off(D0, 3, 0)>(vb), h3 = tr_read<v_rd_off(D0, 3, 1)>(vb);
;   asm volatile("s_waitcnt lgkmcnt(0)" ::: "memory"); SBAR();
;     ...
;   od = __builtin_amdgcn_mfma_f32_32x32x16_bf16(pa0, PK(l0, h0), od, 0, 0, 0);
;   od = __builtin_amdgcn_mfma_f32_32x32x16_bf16(pa1, PK(l1, h1), od, 0, 0, 0);
;   od = __builtin_amdgcn_mfma_f32_32x32x16_bf16(pa2, PK(l2, h2), od, 0, 0, 0);
;   od = __builtin_amdgcn_mfma_f32_32x32x16_bf16(pa3, PK(l3, h3), od, 0, 0, 0);
;     ...
; }
	ds_write_b128 v146, v[158:161] offset:57344
	v_add_co_u32_e32 v146, vcc, s8, v166
	s_mov_b32 s8, 0xfffc0000
	s_nop 0
	v_addc_co_u32_e32 v147, vcc, -1, v167, vcc
	v_add_co_u32_e32 v150, vcc, s8, v166
	s_mov_b32 s8, 0xfb7a0000
	s_nop 0
	v_addc_co_u32_e32 v151, vcc, -1, v167, vcc
	v_add_co_u32_e32 v154, vcc, s8, v166
	s_mov_b32 s8, 0xfb7c0000
	s_nop 0
	v_addc_co_u32_e32 v155, vcc, -1, v167, vcc
	v_add_co_u32_e32 v158, vcc, s8, v166
	global_load_dwordx4 v[146:149], v[146:147], off
	s_nop 0
	global_load_dwordx4 v[150:153], v[150:151], off
	v_addc_co_u32_e32 v159, vcc, -1, v167, vcc
	global_load_dwordx4 v[154:157], v[154:155], off
	s_nop 0
	global_load_dwordx4 v[158:161], v[158:159], off
	v_lshl_add_u32 v218, s9, 14, v181
	ds_read_b64_tr_b16 v[202:203], v218 offset:0
	ds_read_b64_tr_b16 v[204:205], v218 offset:0x800
	ds_read_b64_tr_b16 v[206:207], v218 offset:0x1000
	ds_read_b64_tr_b16 v[208:209], v218 offset:0x1800
	ds_read_b64_tr_b16 v[210:211], v218 offset:0x2000
	ds_read_b64_tr_b16 v[212:213], v218 offset:0x2800
	ds_read_b64_tr_b16 v[214:215], v218 offset:0x3000
	ds_read_b64_tr_b16 v[216:217], v218 offset:0x3800
	s_waitcnt lgkmcnt(6)
	s_nop 0
	v_mfma_f32_32x32x16_bf16 v[2:17], v[82:85], v[202:205], v[2:17]
	ds_read_b64_tr_b16 v[202:203], v218 offset:0x200
	ds_read_b64_tr_b16 v[204:205], v218 offset:0xa00
	s_waitcnt lgkmcnt(6)
	v_mfma_f32_32x32x16_bf16 v[2:17], v[86:89], v[206:209], v[2:17]
	ds_read_b64_tr_b16 v[206:207], v218 offset:0x1200
	ds_read_b64_tr_b16 v[208:209], v218 offset:0x1a00
	s_waitcnt lgkmcnt(6)
	v_mfma_f32_32x32x16_bf16 v[2:17], v[90:93], v[210:213], v[2:17]
	ds_read_b64_tr_b16 v[210:211], v218 offset:0x2200
	ds_read_b64_tr_b16 v[212:213], v218 offset:0x2a00
	s_waitcnt lgkmcnt(6)
	v_mfma_f32_32x32x16_bf16 v[2:17], v[94:97], v[214:217], v[2:17]
	ds_read_b64_tr_b16 v[214:215], v218 offset:0x3200
	ds_read_b64_tr_b16 v[216:217], v218 offset:0x3a00
	s_waitcnt lgkmcnt(6)
	v_mfma_f32_32x32x16_bf16 v[50:65], v[82:85], v[202:205], v[50:65]
	ds_read_b64_tr_b16 v[202:203], v218 offset:0x400
	ds_read_b64_tr_b16 v[204:205], v218 offset:0xc00
	s_waitcnt lgkmcnt(6)
	v_mfma_f32_32x32x16_bf16 v[50:65], v[86:89], v[206:209], v[50:65]
	ds_read_b64_tr_b16 v[206:207], v218 offset:0x1400
	ds_read_b64_tr_b16 v[208:209], v218 offset:0x1c00
	s_waitcnt lgkmcnt(6)
	v_mfma_f32_32x32x16_bf16 v[50:65], v[90:93], v[210:213], v[50:65]
	ds_read_b64_tr_b16 v[210:211], v218 offset:0x2400
	ds_read_b64_tr_b16 v[212:213], v218 offset:0x2c00
	s_waitcnt lgkmcnt(6)
	v_mfma_f32_32x32x16_bf16 v[50:65], v[94:97], v[214:217], v[50:65]
	ds_read_b64_tr_b16 v[214:215], v218 offset:0x3400
	ds_read_b64_tr_b16 v[216:217], v218 offset:0x3c00
	s_waitcnt lgkmcnt(6)
	v_mfma_f32_32x32x16_bf16 v[34:49], v[82:85], v[202:205], v[34:49]
	ds_read_b64_tr_b16 v[202:203], v218 offset:0x600
	ds_read_b64_tr_b16 v[204:205], v218 offset:0xe00
	s_waitcnt lgkmcnt(6)
	v_mfma_f32_32x32x16_bf16 v[34:49], v[86:89], v[206:209], v[34:49]
	ds_read_b64_tr_b16 v[206:207], v218 offset:0x1600
	ds_read_b64_tr_b16 v[208:209], v218 offset:0x1e00
	s_waitcnt lgkmcnt(6)
	v_mfma_f32_32x32x16_bf16 v[34:49], v[90:93], v[210:213], v[34:49]
	ds_read_b64_tr_b16 v[210:211], v218 offset:0x2600
	ds_read_b64_tr_b16 v[212:213], v218 offset:0x2e00
	s_waitcnt lgkmcnt(6)
	v_mfma_f32_32x32x16_bf16 v[34:49], v[94:97], v[214:217], v[34:49]
	ds_read_b64_tr_b16 v[214:215], v218 offset:0x3600
	ds_read_b64_tr_b16 v[216:217], v218 offset:0x3e00
	s_waitcnt lgkmcnt(6)
	v_mfma_f32_32x32x16_bf16 v[18:33], v[82:85], v[202:205], v[18:33]
	v_max_f32_e32 v82, v115, v115
	v_max_f32_e32 v83, v114, v114
	v_max_f32_e32 v82, v83, v82
	v_max3_f32 v82, v82, v116, v117
	v_max3_f32 v82, v82, v118, v119
	v_max3_f32 v82, v82, v120, v121
	v_max3_f32 v82, v82, v122, v123
	s_waitcnt lgkmcnt(4)
	v_mfma_f32_32x32x16_bf16 v[18:33], v[86:89], v[206:209], v[18:33]
	v_max3_f32 v82, v82, v124, v125
	v_max3_f32 v82, v82, v126, v127
	v_max3_f32 v82, v82, v128, v129
	v_max3_f32 v82, v82, v98, v99
	v_max3_f32 v82, v82, v100, v101
	v_max3_f32 v82, v82, v102, v103
	v_max3_f32 v82, v82, v104, v105
	s_waitcnt lgkmcnt(2)
	v_mfma_f32_32x32x16_bf16 v[18:33], v[90:93], v[210:213], v[18:33]
	v_max3_f32 v82, v82, v106, v107
	v_max3_f32 v82, v82, v108, v109
	v_max3_f32 v82, v82, v110, v111
	v_max3_f32 v82, v82, v112, v113
	v_mov_b32_e32 v83, v82
	s_nop 1
	v_permlane32_swap_b32_e32 v82, v83
	s_waitcnt lgkmcnt(0)
	v_mfma_f32_32x32x16_bf16 v[18:33], v[94:97], v[214:217], v[18:33]
	v_max_f32_e32 v83, v83, v83
	v_max_f32_e32 v82, v82, v82
	v_max_f32_e32 v82, v82, v83
	v_cmp_ge_f32_e32 vcc, s0, v82
	s_cmp_eq_u64 vcc, exec
	s_cbranch_scc0 .LBB0_331
	v_mov_b32_e32 v203, 1.0

; #define SBAR() __builtin_amdgcn_sched_barrier(0)
; template <bool FIRST> __device__ __forceinline__ void partialSM_ps(f32x16& p0, f32x16& p1, float& m_reg, float& alpha, f32x16& negm) {
;   float pmax = p0[0];
; #pragma unroll
;   for (int r = 1; r < 16; ++r) pmax = fmaxf(pmax, p0[r]);
; #pragma unroll
;   for (int r = 0; r < 16; ++r) pmax = fmaxf(pmax, p1[r]);
;   { auto rr = __builtin_amdgcn_permlane32_swap(__float_as_uint(pmax), __float_as_uint(pmax), false, false);
;     pmax = fmaxf(__uint_as_float(rr[0]), __uint_as_float(rr[1])); }
;   alpha = 1.f;
;   if (FIRST || !__builtin_expect(__all(pmax <= THRL), 1)) {
; template <int D0> __device__ __forceinline__ void pv_one(f32x16& od, int vb, bf16x8 pa0, bf16x8 pa1, bf16x8 pa2, bf16x8 pa3) {
;   const s16x4 l0 = tr_read<v_rd_off(D0, 0, 0)>(vb), h0 = tr_read<v_rd_off(D0, 0, 1)>(vb), l1 = tr_read<v_rd_off(D0, 1, 0)>(vb), h1 = tr_read<v_rd_off(D0, 1, 1)>(vb);
;   const s16x4 l2 = tr_read<v_rd_off(D0, 2, 0)>(vb), h2 = tr_read<v_rd_off(D0, 2, 1)>(vb), l3 = tr_read<v_rd_off(D0, 3, 0)>(vb), h3 = tr_read<v_rd_off(D0, 3, 1)>(vb);
;   asm volatile("s_waitcnt lgkmcnt(0)" ::: "memory"); SBAR();
;     ...
;   od = __builtin_amdgcn_mfma_f32_32x32x16_bf16(pa0, PK(l0, h0), od, 0, 0, 0);
;   od = __builtin_amdgcn_mfma_f32_32x32x16_bf16(pa1, PK(l1, h1), od, 0, 0, 0);
;   od = __builtin_amdgcn_mfma_f32_32x32x16_bf16(pa2, PK(l2, h2), od, 0, 0, 0);
;   od = __builtin_amdgcn_mfma_f32_32x32x16_bf16(pa3, PK(l3, h3), od, 0, 0, 0);
;     ...
; }
.LBB0_324:
	v_add_u32_e32 v202, s10, v181
	ds_read_b64_tr_b16 v[206:207], v202 offset:0
	ds_read_b64_tr_b16 v[208:209], v202 offset:0x800
	ds_read_b64_tr_b16 v[210:211], v202 offset:0x1000
	ds_read_b64_tr_b16 v[212:213], v202 offset:0x1800
	ds_read_b64_tr_b16 v[214:215], v202 offset:0x2000
	ds_read_b64_tr_b16 v[216:217], v202 offset:0x2800
	ds_read_b64_tr_b16 v[218:219], v202 offset:0x3000
	ds_read_b64_tr_b16 v[220:221], v202 offset:0x3800
	s_waitcnt lgkmcnt(6)
	s_nop 0
	v_mfma_f32_32x32x16_bf16 v[2:17], v[98:101], v[206:209], v[2:17]
	ds_read_b64_tr_b16 v[206:207], v202 offset:0x200
	ds_read_b64_tr_b16 v[208:209], v202 offset:0xa00
	s_waitcnt lgkmcnt(6)
	v_mfma_f32_32x32x16_bf16 v[2:17], v[102:105], v[210:213], v[2:17]
	ds_read_b64_tr_b16 v[210:211], v202 offset:0x1200
	ds_read_b64_tr_b16 v[212:213], v202 offset:0x1a00
	s_waitcnt lgkmcnt(6)
	v_mfma_f32_32x32x16_bf16 v[2:17], v[106:109], v[214:217], v[2:17]
	ds_read_b64_tr_b16 v[214:215], v202 offset:0x2200
	ds_read_b64_tr_b16 v[216:217], v202 offset:0x2a00
	s_waitcnt lgkmcnt(6)
	v_mfma_f32_32x32x16_bf16 v[2:17], v[110:113], v[218:221], v[2:17]
	ds_read_b64_tr_b16 v[218:219], v202 offset:0x3200
	ds_read_b64_tr_b16 v[220:221], v202 offset:0x3a00
	s_waitcnt lgkmcnt(6)
	v_mfma_f32_32x32x16_bf16 v[50:65], v[98:101], v[206:209], v[50:65]
	ds_read_b64_tr_b16 v[206:207], v202 offset:0x400
	ds_read_b64_tr_b16 v[208:209], v202 offset:0xc00
	s_waitcnt lgkmcnt(6)
	v_mfma_f32_32x32x16_bf16 v[50:65], v[102:105], v[210:213], v[50:65]
	ds_read_b64_tr_b16 v[210:211], v202 offset:0x1400
	ds_read_b64_tr_b16 v[212:213], v202 offset:0x1c00
	s_waitcnt lgkmcnt(6)
	v_mfma_f32_32x32x16_bf16 v[50:65], v[106:109], v[214:217], v[50:65]
	ds_read_b64_tr_b16 v[214:215], v202 offset:0x2400
	ds_read_b64_tr_b16 v[216:217], v202 offset:0x2c00
	s_waitcnt lgkmcnt(6)
	v_mfma_f32_32x32x16_bf16 v[50:65], v[110:113], v[218:221], v[50:65]
	ds_read_b64_tr_b16 v[218:219], v202 offset:0x3400
	ds_read_b64_tr_b16 v[220:221], v202 offset:0x3c00
	s_waitcnt lgkmcnt(6)
	v_mfma_f32_32x32x16_bf16 v[34:49], v[98:101], v[206:209], v[34:49]
	ds_read_b64_tr_b16 v[206:207], v202 offset:0x600
	ds_read_b64_tr_b16 v[208:209], v202 offset:0xe00
	s_waitcnt lgkmcnt(6)
	v_mfma_f32_32x32x16_bf16 v[34:49], v[102:105], v[210:213], v[34:49]
	ds_read_b64_tr_b16 v[210:211], v202 offset:0x1600
	ds_read_b64_tr_b16 v[212:213], v202 offset:0x1e00
	s_waitcnt lgkmcnt(6)
	v_mfma_f32_32x32x16_bf16 v[34:49], v[106:109], v[214:217], v[34:49]
	ds_read_b64_tr_b16 v[214:215], v202 offset:0x2600
	ds_read_b64_tr_b16 v[216:217], v202 offset:0x2e00
	s_waitcnt lgkmcnt(6)
	v_mfma_f32_32x32x16_bf16 v[34:49], v[110:113], v[218:221], v[34:49]
	ds_read_b64_tr_b16 v[218:219], v202 offset:0x3600
	ds_read_b64_tr_b16 v[220:221], v202 offset:0x3e00
	s_waitcnt lgkmcnt(6)
	v_mfma_f32_32x32x16_bf16 v[18:33], v[98:101], v[206:209], v[18:33]
	v_max_f32_e32 v98, v115, v115
	v_max_f32_e32 v99, v114, v114
	v_max_f32_e32 v98, v99, v98
	v_max3_f32 v98, v98, v116, v117
	v_max3_f32 v98, v98, v118, v119
	v_max3_f32 v98, v98, v120, v121
	v_max3_f32 v98, v98, v122, v123
	s_waitcnt lgkmcnt(4)
	v_mfma_f32_32x32x16_bf16 v[18:33], v[102:105], v[210:213], v[18:33]
	v_max3_f32 v98, v98, v124, v125
	v_max3_f32 v98, v98, v126, v127
	v_max3_f32 v98, v98, v128, v129
	v_max3_f32 v98, v98, v82, v83
	v_max3_f32 v98, v98, v84, v85
	v_max3_f32 v98, v98, v86, v87
	v_max3_f32 v98, v98, v88, v89
	s_waitcnt lgkmcnt(2)
	v_mfma_f32_32x32x16_bf16 v[18:33], v[106:109], v[214:217], v[18:33]
	v_max3_f32 v98, v98, v90, v91
	v_max3_f32 v98, v98, v92, v93
	v_max3_f32 v98, v98, v94, v95
	v_max3_f32 v98, v98, v96, v97
	v_mov_b32_e32 v99, v98
	s_nop 1
	v_permlane32_swap_b32_e32 v98, v99
	s_waitcnt lgkmcnt(0)
	v_mfma_f32_32x32x16_bf16 v[18:33], v[110:113], v[218:221], v[18:33]
	v_max_f32_e32 v99, v99, v99
	v_max_f32_e32 v98, v98, v98
	v_max_f32_e32 v98, v98, v99
	v_cmp_ge_f32_e32 vcc, s0, v98
	s_cmp_eq_u64 vcc, exec
	v_mov_b32_e32 v202, 1.0
	s_cbranch_scc0 .LBB0_332
